# P5: O-wave V DMA spread between MFMAs, S-wave QK MFMAs woven into softmax VALU; P2: epilogue z loads preloaded
# speedup vs baseline: 1.0048x; 1.0048x over previous
; __device__ __forceinline__ int crow(int r, int hi) { return (r & 3) + 8 * (r >> 2) + 4 * hi; }
; template <int LD, class Mask, class Epi>
; __device__ __forceinline__ void attn_body_simple(const bf16* __restrict__ Qw, const bf16* __restrict__ Kh, const bf16* __restrict__ Vh, int NT, char* lds,
;                                                  const Mask& mask, const Epi& epi, float sink_l2) {
;     ...
;   float rli[16];
; #pragma unroll
;   for (int r = 0; r < 16; ++r) rli[r] = __builtin_amdgcn_rcpf(li_l[crow(r, hi)]);
;   __syncthreads();
;   float* tile = (float*)lds + wid * (32 * 132);
; #pragma unroll
;   for (int r = 0; r < 16; ++r) { const int orow = crow(r, hi);
; #pragma unroll
;     for (int d0 = 0; d0 < 4; ++d0) tile[orow * 132 + d0 * 32 + r32] = o[d0][r] * rli[r]; }
;   asm volatile("s_waitcnt lgkmcnt(0)" ::: "memory");
; #pragma unroll 4
;   for (int it = 0; it < 16; ++it) { const int row = it * 2 + hi, col = r32 * 4; const f32x4v v = *(const f32x4v*)(tile + row * 132 + col); epi.row4(row, col, v); }
.LBB0_166:
	s_or_b64 exec, exec, s[0:1]
	s_waitcnt lgkmcnt(0)
	v_lshl_add_u32 v72, v159, 4, v164
	ds_read_b128 v[64:67], v72
	ds_read_b128 v[68:71], v72 offset:32
	v_lshrrev_b32_e32 v75, 6, v161
	v_lshlrev_b32_e32 v84, 2, v158
	v_mul_u32_u24_e32 v85, 0x840, v159
	s_waitcnt lgkmcnt(1)
	v_rcp_f32_e32 v76, v64
	v_rcp_f32_e32 v77, v65
	v_rcp_f32_e32 v78, v66
	v_rcp_f32_e32 v79, v67
	s_waitcnt lgkmcnt(0)
	v_rcp_f32_e32 v80, v68
	ds_read_b128 v[64:67], v72 offset:64
	v_rcp_f32_e32 v81, v69
	v_rcp_f32_e32 v82, v70
	v_rcp_f32_e32 v83, v71
	ds_read_b128 v[68:71], v72 offset:96
	v_mul_lo_u32 v72, v75, s30
	v_add_u32_e32 v75, 0, v72
	v_add3_u32 v75, v75, v84, v85
	v_mul_f32_e32 v0, v0, v76
	v_mul_f32_e32 v48, v48, v76
	s_waitcnt lgkmcnt(0)
	s_barrier
	ds_write2_b32 v75, v0, v48 offset1:32
	v_mul_f32_e32 v0, v32, v76
	v_mul_f32_e32 v16, v16, v76
	ds_write2_b32 v75, v0, v16 offset0:64 offset1:96
	v_mul_f32_e32 v0, v1, v77
	v_mul_f32_e32 v1, v49, v77
	ds_write2_b32 v75, v0, v1 offset0:132 offset1:164
	v_mul_f32_e32 v0, v33, v77
	v_mul_f32_e32 v1, v17, v77
	ds_write2_b32 v75, v0, v1 offset0:196 offset1:228
	v_mul_f32_e32 v0, v2, v78
	v_mul_f32_e32 v1, v50, v78
	v_add_u32_e32 v2, 0x400, v75
	ds_write2_b32 v2, v0, v1 offset0:8 offset1:40
	v_mul_f32_e32 v0, v34, v78
	v_mul_f32_e32 v1, v18, v78
	ds_write2_b32 v2, v0, v1 offset0:72 offset1:104
	v_mul_f32_e32 v0, v3, v79
	v_mul_f32_e32 v1, v51, v79
	ds_write2_b32 v2, v0, v1 offset0:140 offset1:172
	v_mul_f32_e32 v0, v35, v79
	v_mul_f32_e32 v1, v19, v79
	ds_write2_b32 v2, v0, v1 offset0:204 offset1:236
	v_mul_f32_e32 v0, v4, v80
	v_mul_f32_e32 v1, v52, v80
	v_add_u32_e32 v2, 0x1000, v75
	ds_write2_b32 v2, v0, v1 offset0:32 offset1:64
	v_mul_f32_e32 v0, v36, v80
	v_mul_f32_e32 v1, v20, v80
	ds_write2_b32 v2, v0, v1 offset0:96 offset1:128
	v_mul_f32_e32 v0, v5, v81
	v_mul_f32_e32 v1, v53, v81
	ds_write2_b32 v2, v0, v1 offset0:164 offset1:196
	v_mul_f32_e32 v0, v37, v81
	v_mul_f32_e32 v1, v21, v81
	v_add_u32_e32 v2, 0x1200, v75
	v_rcp_f32_e32 v64, v64
	ds_write2_b32 v2, v0, v1 offset0:100 offset1:132
	v_mul_f32_e32 v0, v6, v82
	v_mul_f32_e32 v1, v54, v82
	v_add_u32_e32 v2, 0x1400, v75
	ds_write2_b32 v2, v0, v1 offset0:40 offset1:72
	v_mul_f32_e32 v0, v38, v82
	v_mul_f32_e32 v1, v22, v82
	v_rcp_f32_e32 v65, v65
	ds_write2_b32 v2, v0, v1 offset0:104 offset1:136
	v_mul_f32_e32 v0, v7, v83
	v_mul_f32_e32 v1, v55, v83
	ds_write2_b32 v2, v0, v1 offset0:172 offset1:204
	v_mul_f32_e32 v0, v39, v83
	v_mul_f32_e32 v1, v23, v83
	v_add_u32_e32 v2, 0x1600, v75
	v_rcp_f32_e32 v66, v66
	ds_write2_b32 v2, v0, v1 offset0:108 offset1:140
	v_mul_f32_e32 v0, v8, v64
	v_mul_f32_e32 v1, v56, v64
	v_add_u32_e32 v2, 0x2000, v75
	ds_write2_b32 v2, v0, v1 offset0:64 offset1:96
	v_mul_f32_e32 v0, v40, v64
	v_mul_f32_e32 v1, v24, v64
	v_rcp_f32_e32 v67, v67
	ds_write2_b32 v2, v0, v1 offset0:128 offset1:160
	v_mul_f32_e32 v0, v9, v65
	v_mul_f32_e32 v1, v57, v65
	ds_write2_b32 v2, v0, v1 offset0:196 offset1:228
	v_mul_f32_e32 v0, v41, v65
	v_mul_f32_e32 v1, v25, v65
	v_add_u32_e32 v2, 0x2400, v75
	v_rcp_f32_e32 v68, v68
	ds_write2_b32 v2, v0, v1 offset0:4 offset1:36
	v_mul_f32_e32 v0, v10, v66
	v_mul_f32_e32 v1, v58, v66
	ds_write2_b32 v2, v0, v1 offset0:72 offset1:104
	v_mul_f32_e32 v0, v42, v66
	v_mul_f32_e32 v1, v26, v66
	v_rcp_f32_e32 v69, v69
	ds_write2_b32 v2, v0, v1 offset0:136 offset1:168
	v_mul_f32_e32 v0, v11, v67
	v_mul_f32_e32 v1, v59, v67
	ds_write2_b32 v2, v0, v1 offset0:204 offset1:236
	v_mul_f32_e32 v0, v43, v67
	v_mul_f32_e32 v1, v27, v67
	v_add_u32_e32 v2, 0x2800, v75
	v_rcp_f32_e32 v70, v70
	ds_write2_b32 v2, v0, v1 offset0:12 offset1:44
	v_mul_f32_e32 v0, v12, v68
	v_mul_f32_e32 v1, v60, v68
	v_add_u32_e32 v2, 0x3000, v75
	ds_write2_b32 v2, v0, v1 offset0:96 offset1:128
	v_mul_f32_e32 v0, v44, v68
	v_mul_f32_e32 v1, v28, v68
	v_rcp_f32_e32 v71, v71
	ds_write2_b32 v2, v0, v1 offset0:160 offset1:192
	v_mul_f32_e32 v0, v13, v69
	v_mul_f32_e32 v1, v61, v69
	v_add_u32_e32 v2, 0x3200, v75
	ds_write2_b32 v2, v0, v1 offset0:100 offset1:132
	v_mul_f32_e32 v0, v45, v69
	v_mul_f32_e32 v1, v29, v69
	v_add_u32_e32 v2, 0x3400, v75
	ds_write2_b32 v2, v0, v1 offset0:36 offset1:68
	v_mul_f32_e32 v0, v14, v70
	v_mul_f32_e32 v1, v62, v70
	ds_write2_b32 v2, v0, v1 offset0:104 offset1:136
	v_mul_f32_e32 v0, v46, v70
	v_mul_f32_e32 v1, v30, v70
	ds_write2_b32 v2, v0, v1 offset0:168 offset1:200
	v_mul_f32_e32 v0, v15, v71
	v_mul_f32_e32 v1, v63, v71
	v_add_u32_e32 v2, 0x3600, v75
	s_and_b32 s0, s4, 3
	ds_write2_b32 v2, v0, v1 offset0:108 offset1:140
	v_mul_f32_e32 v0, v47, v71
	v_mul_f32_e32 v1, v31, v71
	v_add_u32_e32 v2, 0x3800, v75
	s_lshl_b32 s0, s0, 2
	s_and_b32 s1, s3, 2
	ds_write2_b32 v2, v0, v1 offset0:44 offset1:76
	v_add_u32_e32 v2, s38, v155
	s_or_b32 s0, s1, s0
	v_ashrrev_i32_e32 v3, 31, v2
	v_mad_u32_u24 v4, v159, s31, v72
	v_add_u32_e32 v73, s0, v154
	v_lshlrev_b32_e32 v146, 12, v159
	v_lshlrev_b64 v[0:1], 12, v[2:3]
	v_add3_u32 v6, v4, v160, 0
	v_lshlrev_b32_e32 v4, 8, v159
	v_lshl_add_u64 v[0:1], v[146:147], 0, v[0:1]
	v_lshl_or_b32 v146, v73, 21, v4
	v_lshlrev_b64 v[2:3], 8, v[2:3]
	s_waitcnt lgkmcnt(0)
	v_lshl_add_u64 v[2:3], v[146:147], 0, v[2:3]
	v_lshlrev_b32_e32 v74, 7, v73
	v_lshl_or_b32 v2, v158, 3, v2
	v_or3_b32 v0, v0, v74, v84
	v_lshl_add_u64 v[2:3], v[2:3], 0, s[6:7]
	s_mov_b32 s0, 0
	v_lshl_add_u64 v[234:235], s[90:91], 0, v[2:3]
	v_lshl_add_u64 v[236:237], v[234:235], 0, s[10:11]
	v_lshl_add_u64 v[236:237], v[236:237], 0, s[10:11]
	global_load_dwordx2 v[202:203], v[234:235], off offset:-1024
	global_load_dwordx2 v[204:205], v[234:235], off offset:-512
	global_load_dwordx2 v[206:207], v[234:235], off
	global_load_dwordx2 v[208:209], v[234:235], off offset:512
	global_load_dwordx2 v[210:211], v[234:235], off offset:1024
	global_load_dwordx2 v[212:213], v[234:235], off offset:1536
	global_load_dwordx2 v[214:215], v[234:235], off offset:2048
	global_load_dwordx2 v[216:217], v[234:235], off offset:2560
	global_load_dwordx2 v[218:219], v[236:237], off offset:-1024
	global_load_dwordx2 v[220:221], v[236:237], off offset:-512
	global_load_dwordx2 v[222:223], v[236:237], off
	global_load_dwordx2 v[224:225], v[236:237], off offset:512
	global_load_dwordx2 v[226:227], v[236:237], off offset:1024
	global_load_dwordx2 v[228:229], v[236:237], off offset:1536
	global_load_dwordx2 v[230:231], v[236:237], off offset:2048
	global_load_dwordx2 v[232:233], v[236:237], off offset:2560
	s_waitcnt vmcnt(0)
; __device__ __forceinline__ void p2_attn_even(const Args& a, unsigned char* lds_g, LAS unsigned char* lds) {
;     ...
;     for (int it = blockIdx.x; it < 512; it += G) {
;         const int h = it & 15, mg = it >> 4;
;         for (int i = tid; i < 465; i += 512) tbl[i] = rpb[h * 465 + i] * (1.0f / att::SCALE);
;         const int qrow = mg * 4 + (wid >> 1), qcol = (wid & 1) * 32 + r32, tok0 = qrow * 64 + (wid & 1) * 32;
;         int krow0, NT; if (mg == 0) { krow0 = 0; NT = 8; } else if (mg == 31) { krow0 = 120; NT = 8; } else { krow0 = mg * 4 - 4; NT = 12; }
;         int rs = qrow - 4; rs = rs < 0 ? 0 : (rs > 120 ? 120 : rs); int cs = qcol - 8; cs = cs < 0 ? 0 : (cs > 48 ? 48 : cs);
;         att::NAMask mk{qrow, qcol, krow0, rs, cs, tbl};
.LBB0_167:
	v_lshl_add_u64 v[16:17], s[90:91], 0, v[2:3]
	v_mov_b32_e32 v18, v202
	v_mov_b32_e32 v19, v203
	v_add_u32_e32 v7, s0, v6
	ds_read_b128 v[8:11], v7
	ds_read_b128 v[12:15], v7 offset:1056
	v_mov_b32_e32 v22, 0
	v_lshl_add_u64 v[4:5], s[90:91], 0, v[0:1]
	v_add_co_u32_e32 v20, vcc, s34, v4
	s_addk_i32 s0, 0x1080
	s_nop 0
	v_addc_co_u32_e32 v21, vcc, 0, v5, vcc
	v_lshl_add_u64 v[0:1], v[0:1], 0, s[8:9]
	v_lshl_add_u64 v[2:3], v[2:3], 0, s[10:11]
	s_cmpk_lg_i32 s0, 0x4200
	v_lshlrev_b32_e32 v23, 16, v18
	v_and_b32_e32 v18, 0xffff0000, v18
	v_mul_f32_e32 v25, 0xbfb8aa3b, v23
	v_mul_f32_e32 v26, 0xbfb8aa3b, v18
	v_exp_f32_e32 v25, v25
	v_exp_f32_e32 v26, v26
	v_lshlrev_b32_e32 v24, 16, v19
	v_and_b32_e32 v19, 0xffff0000, v19
	v_mul_f32_e32 v27, 0xbfb8aa3b, v24
	v_mul_f32_e32 v28, 0xbfb8aa3b, v19
	v_exp_f32_e32 v27, v27
	v_exp_f32_e32 v28, v28
	v_add_f32_e32 v25, 1.0, v25
	v_add_f32_e32 v26, 1.0, v26
	v_rcp_f32_e32 v25, v25
	v_rcp_f32_e32 v26, v26
	v_add_f32_e32 v27, 1.0, v27
	v_add_f32_e32 v28, 1.0, v28
	v_rcp_f32_e32 v27, v27
	v_rcp_f32_e32 v28, v28
	v_mul_f32_e32 v23, v25, v23
	v_mul_f32_e32 v18, v26, v18
	s_waitcnt lgkmcnt(1)
	v_mul_f32_e32 v8, v8, v23
	v_mul_f32_e32 v9, v9, v18
	v_mul_f32_e32 v8, 0x42800000, v8
	v_mul_f32_e32 v9, 0x42800000, v9
	v_cvt_pk_fp8_f32 v22, v8, v9
	v_mul_f32_e32 v24, v27, v24
	v_mul_f32_e32 v19, v28, v19
	v_mul_f32_e32 v10, v10, v24
	v_mul_f32_e32 v11, v11, v19
	v_mul_f32_e32 v10, 0x42800000, v10
	v_mul_f32_e32 v11, 0x42800000, v11
	v_cvt_pk_fp8_f32 v22, v10, v11 op_sel:[0,0,1]
	v_mov_b32_e32 v18, 0
	v_add_co_u32_e32 v10, vcc, s35, v4
	global_store_dword v[20:21], v22, off
	v_mov_b32_e32 v8, v204
	v_mov_b32_e32 v9, v205
	v_addc_co_u32_e32 v11, vcc, 0, v5, vcc
	v_lshlrev_b32_e32 v19, 16, v8
	v_and_b32_e32 v8, 0xffff0000, v8
	v_mul_f32_e32 v21, 0xbfb8aa3b, v19
	v_mul_f32_e32 v22, 0xbfb8aa3b, v8
	v_exp_f32_e32 v21, v21
	v_exp_f32_e32 v22, v22
	v_lshlrev_b32_e32 v20, 16, v9
	v_and_b32_e32 v9, 0xffff0000, v9
	v_mul_f32_e32 v23, 0xbfb8aa3b, v20
	v_mul_f32_e32 v24, 0xbfb8aa3b, v9
	v_exp_f32_e32 v23, v23
	v_exp_f32_e32 v24, v24
	v_add_f32_e32 v21, 1.0, v21
	v_add_f32_e32 v22, 1.0, v22
	v_rcp_f32_e32 v21, v21
	v_rcp_f32_e32 v22, v22
	v_add_f32_e32 v23, 1.0, v23
	v_add_f32_e32 v24, 1.0, v24
	v_rcp_f32_e32 v23, v23
	v_rcp_f32_e32 v24, v24
	v_mul_f32_e32 v19, v21, v19
	v_mul_f32_e32 v8, v22, v8
	s_waitcnt lgkmcnt(0)
	v_mul_f32_e32 v12, v12, v19
	v_mul_f32_e32 v8, v13, v8
	v_mul_f32_e32 v12, 0x42800000, v12
	v_mul_f32_e32 v8, 0x42800000, v8
	v_cvt_pk_fp8_f32 v18, v12, v8
	v_mul_f32_e32 v20, v23, v20
	v_mul_f32_e32 v9, v24, v9
	v_mul_f32_e32 v13, v14, v20
	v_mul_f32_e32 v9, v15, v9
	v_mul_f32_e32 v13, 0x42800000, v13
	v_mul_f32_e32 v9, 0x42800000, v9
	v_cvt_pk_fp8_f32 v18, v13, v9 op_sel:[0,0,1]
	v_mov_b32_e32 v22, 0
	v_add_co_u32_e32 v20, vcc, s36, v4
	global_store_dword v[10:11], v18, off
	v_mov_b32_e32 v18, v206
	v_mov_b32_e32 v19, v207
	ds_read_b128 v[8:11], v7 offset:2112
	ds_read_b128 v[12:15], v7 offset:3168
	v_addc_co_u32_e32 v21, vcc, 0, v5, vcc
	v_add_co_u32_e32 v4, vcc, 0x27006000, v4
	v_lshlrev_b32_e32 v7, 16, v18
	v_and_b32_e32 v18, 0xffff0000, v18
	v_mul_f32_e32 v24, 0xbfb8aa3b, v7
	v_mul_f32_e32 v25, 0xbfb8aa3b, v18
	v_exp_f32_e32 v24, v24
	v_exp_f32_e32 v25, v25
	v_lshlrev_b32_e32 v23, 16, v19
	v_and_b32_e32 v19, 0xffff0000, v19
	v_mul_f32_e32 v26, 0xbfb8aa3b, v23
	v_mul_f32_e32 v27, 0xbfb8aa3b, v19
	v_exp_f32_e32 v26, v26
	v_exp_f32_e32 v27, v27
	v_add_f32_e32 v24, 1.0, v24
	v_add_f32_e32 v25, 1.0, v25
	v_rcp_f32_e32 v24, v24
	v_rcp_f32_e32 v25, v25
	v_add_f32_e32 v26, 1.0, v26
	v_add_f32_e32 v27, 1.0, v27
	v_rcp_f32_e32 v26, v26
	v_rcp_f32_e32 v27, v27
	v_mul_f32_e32 v7, v24, v7
	v_mul_f32_e32 v18, v25, v18
	s_waitcnt lgkmcnt(1)
	v_mul_f32_e32 v7, v8, v7
	v_mul_f32_e32 v8, v9, v18
	v_mul_f32_e32 v7, 0x42800000, v7
	v_mul_f32_e32 v8, 0x42800000, v8
	v_cvt_pk_fp8_f32 v22, v7, v8
	v_mul_f32_e32 v23, v26, v23
	v_mul_f32_e32 v19, v27, v19
	v_mul_f32_e32 v9, v10, v23
	v_mul_f32_e32 v10, v11, v19
	v_mul_f32_e32 v9, 0x42800000, v9
	v_mul_f32_e32 v10, 0x42800000, v10
	v_cvt_pk_fp8_f32 v22, v9, v10 op_sel:[0,0,1]
	v_mov_b32_e32 v7, 0
	v_addc_co_u32_e32 v5, vcc, 0, v5, vcc
	global_store_dword v[20:21], v22, off
	v_mov_b32_e32 v8, v208
	v_mov_b32_e32 v9, v209
	v_lshlrev_b32_e32 v10, 16, v8
	v_and_b32_e32 v8, 0xffff0000, v8
	v_mul_f32_e32 v16, 0xbfb8aa3b, v10
	v_mul_f32_e32 v17, 0xbfb8aa3b, v8
	v_exp_f32_e32 v16, v16
	v_exp_f32_e32 v17, v17
	v_lshlrev_b32_e32 v11, 16, v9
	v_and_b32_e32 v9, 0xffff0000, v9
	v_mul_f32_e32 v18, 0xbfb8aa3b, v11
	v_mul_f32_e32 v19, 0xbfb8aa3b, v9
	v_exp_f32_e32 v18, v18
	v_exp_f32_e32 v19, v19
	v_add_f32_e32 v16, 1.0, v16
	v_add_f32_e32 v17, 1.0, v17
	v_rcp_f32_e32 v16, v16
	v_rcp_f32_e32 v17, v17
	v_add_f32_e32 v18, 1.0, v18
	v_add_f32_e32 v19, 1.0, v19
	v_rcp_f32_e32 v18, v18
	v_rcp_f32_e32 v19, v19
	v_mul_f32_e32 v10, v16, v10
	v_mul_f32_e32 v8, v17, v8
	s_waitcnt lgkmcnt(0)
	v_mul_f32_e32 v10, v12, v10
	v_mul_f32_e32 v8, v13, v8
	v_mul_f32_e32 v10, 0x42800000, v10
	v_mul_f32_e32 v8, 0x42800000, v8
	v_cvt_pk_fp8_f32 v7, v10, v8
	v_mul_f32_e32 v11, v18, v11
	v_mul_f32_e32 v9, v19, v9
	v_mul_f32_e32 v11, v14, v11
	v_mul_f32_e32 v8, v15, v9
	v_mul_f32_e32 v9, 0x42800000, v11
	v_mul_f32_e32 v8, 0x42800000, v8
	v_cvt_pk_fp8_f32 v7, v9, v8 op_sel:[0,0,1]
	global_store_dword v[4:5], v7, off
	v_mov_b64_e32 v[202:203], v[210:211]
	v_mov_b64_e32 v[204:205], v[212:213]
	v_mov_b64_e32 v[206:207], v[214:215]
	v_mov_b64_e32 v[208:209], v[216:217]
	v_mov_b64_e32 v[210:211], v[218:219]
	v_mov_b64_e32 v[212:213], v[220:221]
	v_mov_b64_e32 v[214:215], v[222:223]
	v_mov_b64_e32 v[216:217], v[224:225]
	v_mov_b64_e32 v[218:219], v[226:227]
	v_mov_b64_e32 v[220:221], v[228:229]
	v_mov_b64_e32 v[222:223], v[230:231]
	v_mov_b64_e32 v[224:225], v[232:233]
	s_cbranch_scc1 .LBB0_167
	s_add_i32 s37, s37, s46
	s_add_i32 s3, s3, s18
	s_cmpk_lt_i32 s37, 0x200
	s_barrier
	s_cbranch_scc1 .LBB0_149
	s_movk_i32 s0, 0x1d1
	v_cmp_gt_u32_e64 s[0:1], s0, v162
	v_and_b32_e32 v152, 32, v152
	v_or_b32_e32 v153, v152, v153
	v_writelane_b32 v242, s0, 32
	v_lshrrev_b32_e32 v145, 7, v162
	v_med3_u32 v0, v153, 8, 56
	v_writelane_b32 v242, s1, 33
	s_add_i32 s0, 0, 0x203a0
	s_add_i32 s3, 0, 0x20000
	v_writelane_b32 v242, s0, 34
	v_add_u32_e32 v154, -8, v0
	s_mov_b32 s43, 0
	v_lshl_add_u32 v155, v162, 2, s3
	v_sub_u32_e32 v144, 0, v153
	v_sub_u32_e32 v156, 0, v145
	v_lshl_or_b32 v157, v145, 6, v152
	v_mov_b32_e32 v158, 0x7c
	v_mov_b32_e32 v147, 0
	s_mov_b32 s94, 0x42b504f3
	v_mov_b32_e32 v159, 0xff800000
	s_mov_b32 s2, s96
	s_mov_b32 s92, s96
	v_writelane_b32 v242, s96, 35
	v_writelane_b32 v242, s47, 36

; __device__ __forceinline__ int crow(int r, int hi) { return (r & 3) + 8 * (r >> 2) + 4 * hi; }
; template <int LD, class Mask, class Epi>
; __device__ __forceinline__ void attn_body_simple(const bf16* __restrict__ Qw, const bf16* __restrict__ Kh, const bf16* __restrict__ Vh, int NT, char* lds,
;                                                  const Mask& mask, const Epi& epi, float sink_l2) {
;     ...
;   float rli[16];
; #pragma unroll
;   for (int r = 0; r < 16; ++r) rli[r] = __builtin_amdgcn_rcpf(li_l[crow(r, hi)]);
;   __syncthreads();
;   float* tile = (float*)lds + wid * (32 * 132);
; #pragma unroll
;   for (int r = 0; r < 16; ++r) { const int orow = crow(r, hi);
; #pragma unroll
;     for (int d0 = 0; d0 < 4; ++d0) tile[orow * 132 + d0 * 32 + r32] = o[d0][r] * rli[r]; }
;   asm volatile("s_waitcnt lgkmcnt(0)" ::: "memory");
; #pragma unroll 4
;   for (int it = 0; it < 16; ++it) { const int row = it * 2 + hi, col = r32 * 4; const f32x4v v = *(const f32x4v*)(tile + row * 132 + col); epi.row4(row, col, v); }
.LBB0_252:
	s_or_b64 exec, exec, s[6:7]
	s_waitcnt lgkmcnt(0)
	v_add_u32_e32 v72, v164, v148
	ds_read_b128 v[64:67], v72
	ds_read_b128 v[68:71], v72 offset:32
	v_lshrrev_b32_e32 v73, 6, v163
	s_movk_i32 s1, 0x4200
	v_readlane_b32 s0, v242, 37
	s_waitcnt lgkmcnt(1)
	v_rcp_f32_e32 v74, v64
	v_rcp_f32_e32 v75, v65
	v_rcp_f32_e32 v76, v66
	v_rcp_f32_e32 v77, v67
	s_waitcnt lgkmcnt(0)
	v_rcp_f32_e32 v78, v68
	ds_read_b128 v[64:67], v72 offset:64
	v_rcp_f32_e32 v79, v69
	v_rcp_f32_e32 v80, v70
	v_rcp_f32_e32 v81, v71
	ds_read_b128 v[68:71], v72 offset:96
	v_mul_lo_u32 v72, v73, s1
	v_lshlrev_b32_e32 v73, 2, v160
	v_add3_u32 v82, 0, v72, v73
	s_movk_i32 s1, 0x840
	v_mad_u32_u24 v83, v161, s1, v82
	v_mul_f32_e32 v0, v0, v74
	v_mul_f32_e32 v48, v48, v74
	s_waitcnt lgkmcnt(0)
	s_barrier
	ds_write2_b32 v83, v0, v48 offset1:32
	v_mul_f32_e32 v0, v16, v74
	v_mul_f32_e32 v16, v32, v74
	s_movk_i32 s1, 0x210
	ds_write2_b32 v83, v0, v16 offset0:64 offset1:96
	v_mad_u32_u24 v0, v165, s1, v82
	v_mul_f32_e32 v1, v1, v75
	v_mul_f32_e32 v16, v49, v75
	ds_write2_b32 v0, v1, v16 offset1:32
	v_mul_f32_e32 v1, v17, v75
	v_mul_f32_e32 v16, v33, v75
	ds_write2_b32 v0, v1, v16 offset0:64 offset1:96
	v_mul_f32_e32 v1, v2, v76
	v_mul_f32_e32 v2, v50, v76
	ds_write2_b32 v0, v1, v2 offset0:132 offset1:164
	v_mul_f32_e32 v1, v18, v76
	v_mul_f32_e32 v2, v34, v76
	ds_write2_b32 v0, v1, v2 offset0:196 offset1:228
	v_mul_f32_e32 v1, v3, v77
	v_mul_f32_e32 v2, v51, v77
	v_add_u32_e32 v3, 0x400, v0
	ds_write2_b32 v3, v1, v2 offset0:8 offset1:40
	v_mul_f32_e32 v1, v19, v77
	v_mul_f32_e32 v2, v35, v77
	ds_write2_b32 v3, v1, v2 offset0:72 offset1:104
	v_mul_f32_e32 v1, v4, v78
	v_mul_f32_e32 v2, v52, v78
	v_add_u32_e32 v3, 0xc00, v0
	ds_write2_b32 v3, v1, v2 offset0:156 offset1:188
	v_mul_f32_e32 v1, v20, v78
	v_mul_f32_e32 v2, v36, v78
	ds_write2_b32 v3, v1, v2 offset0:220 offset1:252
	v_mul_f32_e32 v1, v5, v79
	v_mul_f32_e32 v2, v53, v79
	v_add_u32_e32 v3, 0x1000, v0
	ds_write2_b32 v3, v1, v2 offset0:32 offset1:64
	v_mul_f32_e32 v1, v21, v79
	v_mul_f32_e32 v2, v37, v79
	v_rcp_f32_e32 v64, v64
	ds_write2_b32 v3, v1, v2 offset0:96 offset1:128
	v_mul_f32_e32 v1, v6, v80
	v_mul_f32_e32 v2, v54, v80
	ds_write2_b32 v3, v1, v2 offset0:164 offset1:196
	v_mul_f32_e32 v1, v22, v80
	v_mul_f32_e32 v2, v38, v80
	v_add_u32_e32 v3, 0x1200, v0
	v_rcp_f32_e32 v65, v65
	ds_write2_b32 v3, v1, v2 offset0:100 offset1:132
	v_mul_f32_e32 v1, v7, v81
	v_mul_f32_e32 v2, v55, v81
	v_add_u32_e32 v3, 0x1400, v0
	ds_write2_b32 v3, v1, v2 offset0:40 offset1:72
	v_mul_f32_e32 v1, v23, v81
	v_mul_f32_e32 v2, v39, v81
	v_rcp_f32_e32 v66, v66
	ds_write2_b32 v3, v1, v2 offset0:104 offset1:136
	v_mul_f32_e32 v1, v8, v64
	v_mul_f32_e32 v2, v56, v64
	v_add_u32_e32 v3, 0x1c00, v0
	ds_write2_b32 v3, v1, v2 offset0:188 offset1:220
	v_mul_f32_e32 v1, v24, v64
	v_mul_f32_e32 v2, v40, v64
	v_add_u32_e32 v3, 0x1e00, v0
	v_rcp_f32_e32 v67, v67
	ds_write2_b32 v3, v1, v2 offset0:124 offset1:156
	v_mul_f32_e32 v1, v9, v65
	v_mul_f32_e32 v2, v57, v65
	v_add_u32_e32 v3, 0x2000, v0
	ds_write2_b32 v3, v1, v2 offset0:64 offset1:96
	v_mul_f32_e32 v1, v25, v65
	v_mul_f32_e32 v2, v41, v65
	v_rcp_f32_e32 v68, v68
	ds_write2_b32 v3, v1, v2 offset0:128 offset1:160
	v_mul_f32_e32 v1, v10, v66
	v_mul_f32_e32 v2, v58, v66
	ds_write2_b32 v3, v1, v2 offset0:196 offset1:228
	v_mul_f32_e32 v1, v26, v66
	v_mul_f32_e32 v2, v42, v66
	v_add_u32_e32 v3, 0x2400, v0
	v_rcp_f32_e32 v69, v69
	ds_write2_b32 v3, v1, v2 offset0:4 offset1:36
	v_mul_f32_e32 v1, v11, v67
	v_mul_f32_e32 v2, v59, v67
	ds_write2_b32 v3, v1, v2 offset0:72 offset1:104
	v_mul_f32_e32 v1, v27, v67
	v_mul_f32_e32 v2, v43, v67
	v_rcp_f32_e32 v70, v70
	ds_write2_b32 v3, v1, v2 offset0:136 offset1:168
	v_mul_f32_e32 v1, v12, v68
	v_mul_f32_e32 v2, v60, v68
	v_add_u32_e32 v3, 0x2c00, v0
	ds_write2_b32 v3, v1, v2 offset0:220 offset1:252
	v_mul_f32_e32 v1, v28, v68
	v_mul_f32_e32 v2, v44, v68
	v_add_u32_e32 v3, 0x3000, v0
	v_rcp_f32_e32 v71, v71
	ds_write2_b32 v3, v1, v2 offset0:28 offset1:60
	v_mul_f32_e32 v1, v13, v69
	v_mul_f32_e32 v2, v61, v69
	ds_write2_b32 v3, v1, v2 offset0:96 offset1:128
	v_mul_f32_e32 v1, v29, v69
	v_mul_f32_e32 v2, v45, v69
	ds_write2_b32 v3, v1, v2 offset0:160 offset1:192
	v_mul_f32_e32 v1, v14, v70
	v_mul_f32_e32 v2, v62, v70
	v_add_u32_e32 v3, 0x3200, v0
	ds_write2_b32 v3, v1, v2 offset0:100 offset1:132
	v_mul_f32_e32 v1, v30, v70
	v_mul_f32_e32 v2, v46, v70
	v_add_u32_e32 v0, 0x3400, v0
	ds_write2_b32 v0, v1, v2 offset0:36 offset1:68
	v_mul_f32_e32 v1, v15, v71
	v_mul_f32_e32 v2, v63, v71
	ds_write2_b32 v0, v1, v2 offset0:104 offset1:136
	v_mul_f32_e32 v1, v31, v71
	v_mul_f32_e32 v2, v47, v71
	ds_write2_b32 v0, v1, v2 offset0:168 offset1:200
	v_lshl_add_u32 v2, s95, 8, v157
	v_ashrrev_i32_e32 v3, 31, v2
	v_lshlrev_b32_e32 v146, 12, v161
	v_lshlrev_b64 v[0:1], 12, v[2:3]
	s_lshl_b32 s0, s0, 7
	v_lshl_add_u64 v[0:1], v[146:147], 0, v[0:1]
	v_or3_b32 v0, v0, s0, v73
	s_add_u32 s0, s42, 0x22000400
	v_mad_u32_u24 v4, v161, s1, v72
	s_addc_u32 s1, 0, 0
	v_lshlrev_b32_e32 v146, 8, v161
	s_waitcnt lgkmcnt(0)
	v_add3_u32 v6, v4, v149, 0
	v_lshl_add_u64 v[4:5], s[0:1], 0, v[146:147]
	v_lshlrev_b64 v[2:3], 8, v[2:3]
	v_lshl_add_u64 v[2:3], v[4:5], 0, v[2:3]
	v_lshlrev_b32_e32 v146, 3, v160
	v_lshl_add_u64 v[2:3], v[2:3], 0, v[146:147]
	s_mov_b32 s0, 0
	s_mov_b64 s[6:7], 0x800
	v_lshl_add_u64 v[128:129], s[90:91], 0, v[2:3]
	v_lshl_add_u64 v[130:131], v[128:129], 0, s[6:7]
	v_lshl_add_u64 v[130:131], v[130:131], 0, s[6:7]
	global_load_dwordx2 v[96:97], v[128:129], off offset:-1024
	global_load_dwordx2 v[98:99], v[128:129], off offset:-512
	global_load_dwordx2 v[100:101], v[128:129], off
	global_load_dwordx2 v[102:103], v[128:129], off offset:512
	global_load_dwordx2 v[104:105], v[128:129], off offset:1024
	global_load_dwordx2 v[106:107], v[128:129], off offset:1536
	global_load_dwordx2 v[108:109], v[128:129], off offset:2048
	global_load_dwordx2 v[110:111], v[128:129], off offset:2560
	global_load_dwordx2 v[112:113], v[130:131], off offset:-1024
	global_load_dwordx2 v[114:115], v[130:131], off offset:-512
	global_load_dwordx2 v[116:117], v[130:131], off
	global_load_dwordx2 v[118:119], v[130:131], off offset:512
	global_load_dwordx2 v[120:121], v[130:131], off offset:1024
	global_load_dwordx2 v[122:123], v[130:131], off offset:1536
	global_load_dwordx2 v[124:125], v[130:131], off offset:2048
	global_load_dwordx2 v[126:127], v[130:131], off offset:2560
	s_waitcnt vmcnt(0)
; template <int LD, class Mask, class Epi>
; __device__ __forceinline__ void attn_body_simple(const bf16* __restrict__ Qw, const bf16* __restrict__ Kh, const bf16* __restrict__ Vh, int NT, char* lds,
;                                                  const Mask& mask, const Epi& epi, float sink_l2) {
;     ...
;   for (int it = 0; it < 16; ++it) { const int row = it * 2 + hi, col = r32 * 4; const f32x4v v = *(const f32x4v*)(tile + row * 132 + col); epi.row4(row, col, v); }
.LBB0_253:
	v_lshl_add_u64 v[16:17], s[90:91], 0, v[2:3]
	v_mov_b32_e32 v18, v96
	v_mov_b32_e32 v19, v97
	v_add_u32_e32 v7, s0, v6
	ds_read_b128 v[8:11], v7
	ds_read_b128 v[12:15], v7 offset:1056
	v_mov_b32_e32 v22, 0
	v_lshl_add_u64 v[4:5], s[90:91], 0, v[0:1]
	s_mov_b32 s1, 0x27000000
	v_add_co_u32_e32 v20, vcc, s1, v4
	s_mov_b32 s1, 0x27002000
	s_nop 0
	v_addc_co_u32_e32 v21, vcc, 0, v5, vcc
	s_addk_i32 s0, 0x1080
	s_mov_b64 s[4:5], 0x8000
	s_mov_b64 s[6:7], 0x800
	v_lshl_add_u64 v[0:1], v[0:1], 0, s[4:5]
	v_lshl_add_u64 v[2:3], v[2:3], 0, s[6:7]
	s_cmpk_lg_i32 s0, 0x4200
	v_lshlrev_b32_e32 v23, 16, v18
	v_and_b32_e32 v18, 0xffff0000, v18
	v_mul_f32_e32 v25, 0xbfb8aa3b, v23
	v_mul_f32_e32 v26, 0xbfb8aa3b, v18
	v_exp_f32_e32 v25, v25
	v_exp_f32_e32 v26, v26
	v_lshlrev_b32_e32 v24, 16, v19
	v_and_b32_e32 v19, 0xffff0000, v19
	v_mul_f32_e32 v27, 0xbfb8aa3b, v24
	v_mul_f32_e32 v28, 0xbfb8aa3b, v19
	v_exp_f32_e32 v27, v27
	v_exp_f32_e32 v28, v28
	v_add_f32_e32 v25, 1.0, v25
	v_add_f32_e32 v26, 1.0, v26
	v_rcp_f32_e32 v25, v25
	v_rcp_f32_e32 v26, v26
	v_add_f32_e32 v27, 1.0, v27
	v_add_f32_e32 v28, 1.0, v28
	v_rcp_f32_e32 v27, v27
	v_rcp_f32_e32 v28, v28
	v_mul_f32_e32 v23, v25, v23
	v_mul_f32_e32 v18, v26, v18
	s_waitcnt lgkmcnt(1)
	v_mul_f32_e32 v8, v8, v23
	v_mul_f32_e32 v9, v9, v18
	v_mul_f32_e32 v8, 0x42800000, v8
	v_mul_f32_e32 v9, 0x42800000, v9
	v_cvt_pk_fp8_f32 v22, v8, v9
	v_mul_f32_e32 v24, v27, v24
	v_mul_f32_e32 v19, v28, v19
	v_mul_f32_e32 v10, v10, v24
	v_mul_f32_e32 v11, v11, v19
	v_mul_f32_e32 v10, 0x42800000, v10
	v_mul_f32_e32 v11, 0x42800000, v11
	v_cvt_pk_fp8_f32 v22, v10, v11 op_sel:[0,0,1]
	v_mov_b32_e32 v18, 0
	v_add_co_u32_e32 v10, vcc, s1, v4
	global_store_dword v[20:21], v22, off offset:2048
	v_mov_b32_e32 v8, v98
	v_mov_b32_e32 v9, v99
	v_addc_co_u32_e32 v11, vcc, 0, v5, vcc
	s_mov_b32 s1, 0x27004000
	v_lshlrev_b32_e32 v19, 16, v8
	v_and_b32_e32 v8, 0xffff0000, v8
	v_mul_f32_e32 v21, 0xbfb8aa3b, v19
	v_mul_f32_e32 v22, 0xbfb8aa3b, v8
	v_exp_f32_e32 v21, v21
	v_exp_f32_e32 v22, v22
	v_lshlrev_b32_e32 v20, 16, v9
	v_and_b32_e32 v9, 0xffff0000, v9
	v_mul_f32_e32 v23, 0xbfb8aa3b, v20
	v_mul_f32_e32 v24, 0xbfb8aa3b, v9
	v_exp_f32_e32 v23, v23
	v_exp_f32_e32 v24, v24
	v_add_f32_e32 v21, 1.0, v21
	v_add_f32_e32 v22, 1.0, v22
	v_rcp_f32_e32 v21, v21
	v_rcp_f32_e32 v22, v22
	v_add_f32_e32 v23, 1.0, v23
	v_add_f32_e32 v24, 1.0, v24
	v_rcp_f32_e32 v23, v23
	v_rcp_f32_e32 v24, v24
	v_mul_f32_e32 v19, v21, v19
	v_mul_f32_e32 v8, v22, v8
	s_waitcnt lgkmcnt(0)
	v_mul_f32_e32 v12, v12, v19
	v_mul_f32_e32 v8, v13, v8
	v_mul_f32_e32 v12, 0x42800000, v12
	v_mul_f32_e32 v8, 0x42800000, v8
	v_cvt_pk_fp8_f32 v18, v12, v8
	v_mul_f32_e32 v20, v23, v20
	v_mul_f32_e32 v9, v24, v9
	v_mul_f32_e32 v13, v14, v20
	v_mul_f32_e32 v9, v15, v9
	v_mul_f32_e32 v13, 0x42800000, v13
	v_mul_f32_e32 v9, 0x42800000, v9
	v_cvt_pk_fp8_f32 v18, v13, v9 op_sel:[0,0,1]
	v_mov_b32_e32 v22, 0
	v_add_co_u32_e32 v20, vcc, s1, v4
	global_store_dword v[10:11], v18, off offset:2048
	v_mov_b32_e32 v18, v100
	v_mov_b32_e32 v19, v101
	ds_read_b128 v[8:11], v7 offset:2112
	ds_read_b128 v[12:15], v7 offset:3168
	v_addc_co_u32_e32 v21, vcc, 0, v5, vcc
	v_add_co_u32_e32 v4, vcc, 0x27006000, v4
	v_lshlrev_b32_e32 v7, 16, v18
	v_and_b32_e32 v18, 0xffff0000, v18
	v_mul_f32_e32 v24, 0xbfb8aa3b, v7
	v_mul_f32_e32 v25, 0xbfb8aa3b, v18
	v_exp_f32_e32 v24, v24
	v_exp_f32_e32 v25, v25
	v_lshlrev_b32_e32 v23, 16, v19
	v_and_b32_e32 v19, 0xffff0000, v19
	v_mul_f32_e32 v26, 0xbfb8aa3b, v23
	v_mul_f32_e32 v27, 0xbfb8aa3b, v19
	v_exp_f32_e32 v26, v26
	v_exp_f32_e32 v27, v27
	v_add_f32_e32 v24, 1.0, v24
	v_add_f32_e32 v25, 1.0, v25
	v_rcp_f32_e32 v24, v24
	v_rcp_f32_e32 v25, v25
	v_add_f32_e32 v26, 1.0, v26
	v_add_f32_e32 v27, 1.0, v27
	v_rcp_f32_e32 v26, v26
	v_rcp_f32_e32 v27, v27
	v_mul_f32_e32 v7, v24, v7
	v_mul_f32_e32 v18, v25, v18
	s_waitcnt lgkmcnt(1)
	v_mul_f32_e32 v7, v8, v7
	v_mul_f32_e32 v8, v9, v18
	v_mul_f32_e32 v7, 0x42800000, v7
	v_mul_f32_e32 v8, 0x42800000, v8
	v_cvt_pk_fp8_f32 v22, v7, v8
	v_mul_f32_e32 v23, v26, v23
	v_mul_f32_e32 v19, v27, v19
	v_mul_f32_e32 v9, v10, v23
	v_mul_f32_e32 v10, v11, v19
	v_mul_f32_e32 v9, 0x42800000, v9
	v_mul_f32_e32 v10, 0x42800000, v10
	v_cvt_pk_fp8_f32 v22, v9, v10 op_sel:[0,0,1]
	v_mov_b32_e32 v7, 0
	v_addc_co_u32_e32 v5, vcc, 0, v5, vcc
	global_store_dword v[20:21], v22, off offset:2048
	v_mov_b32_e32 v8, v102
	v_mov_b32_e32 v9, v103
	v_lshlrev_b32_e32 v10, 16, v8
	v_and_b32_e32 v8, 0xffff0000, v8
	v_mul_f32_e32 v16, 0xbfb8aa3b, v10
	v_mul_f32_e32 v17, 0xbfb8aa3b, v8
	v_exp_f32_e32 v16, v16
	v_exp_f32_e32 v17, v17
	v_lshlrev_b32_e32 v11, 16, v9
	v_and_b32_e32 v9, 0xffff0000, v9
	v_mul_f32_e32 v18, 0xbfb8aa3b, v11
	v_mul_f32_e32 v19, 0xbfb8aa3b, v9
	v_exp_f32_e32 v18, v18
	v_exp_f32_e32 v19, v19
	v_add_f32_e32 v16, 1.0, v16
	v_add_f32_e32 v17, 1.0, v17
	v_rcp_f32_e32 v16, v16
	v_rcp_f32_e32 v17, v17
	v_add_f32_e32 v18, 1.0, v18
	v_add_f32_e32 v19, 1.0, v19
	v_rcp_f32_e32 v18, v18
	v_rcp_f32_e32 v19, v19
	v_mul_f32_e32 v10, v16, v10
	v_mul_f32_e32 v8, v17, v8
	s_waitcnt lgkmcnt(0)
	v_mul_f32_e32 v10, v12, v10
	v_mul_f32_e32 v8, v13, v8
	v_mul_f32_e32 v10, 0x42800000, v10
	v_mul_f32_e32 v8, 0x42800000, v8
	v_cvt_pk_fp8_f32 v7, v10, v8
	v_mul_f32_e32 v11, v18, v11
	v_mul_f32_e32 v9, v19, v9
	v_mul_f32_e32 v11, v14, v11
	v_mul_f32_e32 v8, v15, v9
	v_mul_f32_e32 v9, 0x42800000, v11
	v_mul_f32_e32 v8, 0x42800000, v8
	v_cvt_pk_fp8_f32 v7, v9, v8 op_sel:[0,0,1]
	global_store_dword v[4:5], v7, off offset:2048
	v_mov_b64_e32 v[96:97], v[104:105]
	v_mov_b64_e32 v[98:99], v[106:107]
	v_mov_b64_e32 v[100:101], v[108:109]
	v_mov_b64_e32 v[102:103], v[110:111]
	v_mov_b64_e32 v[104:105], v[112:113]
	v_mov_b64_e32 v[106:107], v[114:115]
	v_mov_b64_e32 v[108:109], v[116:117]
	v_mov_b64_e32 v[110:111], v[118:119]
	v_mov_b64_e32 v[112:113], v[120:121]
	v_mov_b64_e32 v[114:115], v[122:123]
	v_mov_b64_e32 v[116:117], v[124:125]
	v_mov_b64_e32 v[118:119], v[126:127]
	s_cbranch_scc1 .LBB0_253
	v_readlane_b32 s4, v242, 26
	v_readlane_b32 s6, v242, 28
	s_add_i32 s92, s92, s6
	s_add_i32 s2, s2, s6
	s_cmpk_lt_i32 s92, 0x200
	s_barrier
	v_readlane_b32 s5, v242, 27
	v_readlane_b32 s7, v242, 29
	s_cbranch_scc1 .LBB0_170

; #define SBAR() __builtin_amdgcn_sched_barrier(0)
; __device__ __forceinline__ int crow(int r, int hi) { return (r & 3) + 8 * (r >> 2) + 4 * hi; }
; #define RS_BAR() do { asm volatile("s_waitcnt lgkmcnt(0)" ::: "memory"); __builtin_amdgcn_s_barrier(); asm volatile("" ::: "memory"); } while (0)
; #define VM0() asm volatile("s_waitcnt vmcnt(0)" ::: "memory")
; #define VM0() asm volatile("s_waitcnt vmcnt(0)" ::: "memory")
; #define VMMA(OD, F) do { OD = __builtin_amdgcn_mfma_f32_32x32x16_bf16(pa0, PKF(F[0], F[1]), OD, 0, 0, 0); OD = __builtin_amdgcn_mfma_f32_32x32x16_bf16(pa1, PKF(F[2], F[3]), OD, 0, 0, 0); \
;       OD = __builtin_amdgcn_mfma_f32_32x32x16_bf16(pa2, PKF(F[4], F[5]), OD, 0, 0, 0); OD = __builtin_amdgcn_mfma_f32_32x32x16_bf16(pa3, PKF(F[6], F[7]), OD, 0, 0, 0); } while (0)
; template <class Epi>
; __device__ __forceinline__ void attn_rs_body(const bf16* __restrict__ Qb, const bf16* __restrict__ Kc, const bf16* __restrict__ V0c, const bf16* __restrict__ V1c, int NT, char* lds, const Epi& epi) {
;     ...
;     RS_BAR();
;     RS_BAR();
;     VDMA(0, 0); VM0();
;     RS_BAR();
;     ...
;     for (int j = 1; j <= NT; ++j) {
;       const int b = (j - 1) & 1;
;       const char* Pb = Pl + b * 16384;
;       const bf16x8 pa0 = *(const bf16x8*)(Pb), pa1 = *(const bf16x8*)(Pb + 1024), pa2 = *(const bf16x8*)(Pb + 2048), pa3 = *(const bf16x8*)(Pb + 3072);
;       const float flag = al[b * 256 + 32];
;       if (__builtin_amdgcn_readfirstlane(__float_as_uint(flag)) != 0u) {
;         float av[16];
; #pragma unroll
;         for (int r = 0; r < 16; ++r) av[r] = al[b * 256 + crow(r, hi)];
; #pragma unroll
;         for (int d = 0; d < 8; ++d)
; #pragma unroll
;           for (int r = 0; r < 16; ++r) o[d][r] *= av[r];
;       }
;       const int vb = vb0 + b * 32768;
;       s16x4 fa[8], fb[8];
;       { const int tv = j < NT ? j : NT - 1; VDMA(tv, b ^ 1); }
;       asm volatile("s_waitcnt lgkmcnt(0)" ::: "memory"); SBAR();
;       VRD(fa, 0, 0); VRD(fb, 1, 0); LW(8); VMMA(o[0], fa);
;       VRD(fa, 2, 0); LW(8); VMMA(o[1], fb);
;       VRD(fb, 3, 0); LW(8); VMMA(o[2], fa);
;       VRD(fa, 0, 1); LW(8); VMMA(o[3], fb);
;       VRD(fb, 1, 1); LW(8); VMMA(o[4], fa);
;       VRD(fa, 2, 1); LW(8); VMMA(o[5], fb);
;       VRD(fb, 3, 1); LW(8); VMMA(o[6], fa);
;       LW(0); VMMA(o[7], fb);
;       VM0(); RS_BAR();
.LBB0_500:
	s_lshl_b32 s72, s72, 15
	v_lshl_add_u64 v[244:245], v[176:177], 0, s[48:49]
	s_add_i32 s72, s51, s72
	v_lshl_add_u64 v[246:247], v[174:175], 0, s[48:49]
	v_lshl_add_u32 v0, s71, 15, v182
	s_waitcnt lgkmcnt(0)
	ds_read_b64_tr_b16 v[146:147], v0 offset:0
	ds_read_b64_tr_b16 v[148:149], v0 offset:0x800
	ds_read_b64_tr_b16 v[150:151], v0 offset:0x1000
	ds_read_b64_tr_b16 v[152:153], v0 offset:0x1800
	ds_read_b64_tr_b16 v[154:155], v0 offset:0x2000
	ds_read_b64_tr_b16 v[156:157], v0 offset:0x2800
	ds_read_b64_tr_b16 v[158:159], v0 offset:0x3000
	ds_read_b64_tr_b16 v[160:161], v0 offset:0x3800
	ds_read_b64_tr_b16 v[184:185], v0 offset:0x200
	ds_read_b64_tr_b16 v[186:187], v0 offset:0xa00
	ds_read_b64_tr_b16 v[188:189], v0 offset:0x1200
	ds_read_b64_tr_b16 v[190:191], v0 offset:0x1a00
	ds_read_b64_tr_b16 v[192:193], v0 offset:0x2200
	ds_read_b64_tr_b16 v[194:195], v0 offset:0x2a00
	ds_read_b64_tr_b16 v[196:197], v0 offset:0x3200
	ds_read_b64_tr_b16 v[198:199], v0 offset:0x3a00
	s_add_i32 m0, s72, 0x8000
	v_lshl_add_u64 v[248:249], v[244:245], 0, s[12:13]
	global_load_lds_dwordx4 v[248:249], off
	s_add_i32 m0, s72, 0xc000
	v_lshl_add_u64 v[250:251], v[244:245], 0, s[14:15]
	global_load_lds_dwordx4 v[250:251], off
	s_waitcnt lgkmcnt(8)
	s_nop 0
	v_mfma_f32_32x32x16_bf16 v[114:129], v[142:145], v[146:149], v[114:129]
	ds_read_b64_tr_b16 v[146:147], v0 offset:0x400
	ds_read_b64_tr_b16 v[148:149], v0 offset:0xc00
	v_mfma_f32_32x32x16_bf16 v[114:129], v[138:141], v[150:153], v[114:129]
	ds_read_b64_tr_b16 v[150:151], v0 offset:0x1400
	ds_read_b64_tr_b16 v[152:153], v0 offset:0x1c00
	s_add_i32 m0, s72, 0x8400
	v_lshl_add_u64 v[248:249], v[244:245], 0, s[16:17]
	global_load_lds_dwordx4 v[248:249], off
	v_mfma_f32_32x32x16_bf16 v[114:129], v[134:137], v[154:157], v[114:129]
	ds_read_b64_tr_b16 v[154:155], v0 offset:0x2400
	ds_read_b64_tr_b16 v[156:157], v0 offset:0x2c00
	v_mfma_f32_32x32x16_bf16 v[114:129], v[130:133], v[158:161], v[114:129]
	ds_read_b64_tr_b16 v[158:159], v0 offset:0x3400
	ds_read_b64_tr_b16 v[160:161], v0 offset:0x3c00
	s_waitcnt lgkmcnt(8)
	s_add_i32 m0, s72, 0xc400
	v_lshl_add_u64 v[250:251], v[244:245], 0, s[18:19]
	global_load_lds_dwordx4 v[250:251], off
	v_mfma_f32_32x32x16_bf16 v[98:113], v[142:145], v[184:187], v[98:113]
	ds_read_b64_tr_b16 v[184:185], v0 offset:0x600
	ds_read_b64_tr_b16 v[186:187], v0 offset:0xe00
	v_mfma_f32_32x32x16_bf16 v[98:113], v[138:141], v[188:191], v[98:113]
	ds_read_b64_tr_b16 v[188:189], v0 offset:0x1600
	ds_read_b64_tr_b16 v[190:191], v0 offset:0x1e00
	s_add_i32 m0, s72, 0x8800
	v_lshl_add_u64 v[248:249], v[246:247], 0, s[12:13]
	global_load_lds_dwordx4 v[248:249], off
	v_mfma_f32_32x32x16_bf16 v[98:113], v[134:137], v[192:195], v[98:113]
	ds_read_b64_tr_b16 v[192:193], v0 offset:0x2600
	ds_read_b64_tr_b16 v[194:195], v0 offset:0x2e00
	v_mfma_f32_32x32x16_bf16 v[98:113], v[130:133], v[196:199], v[98:113]
	ds_read_b64_tr_b16 v[196:197], v0 offset:0x3600
	ds_read_b64_tr_b16 v[198:199], v0 offset:0x3e00
	s_waitcnt lgkmcnt(8)
	s_add_i32 m0, s72, 0xc800
	v_lshl_add_u64 v[250:251], v[246:247], 0, s[14:15]
	global_load_lds_dwordx4 v[250:251], off
	v_mfma_f32_32x32x16_bf16 v[82:97], v[142:145], v[146:149], v[82:97]
	ds_read_b64_tr_b16 v[146:147], v0 offset:0x4000
	ds_read_b64_tr_b16 v[148:149], v0 offset:0x4800
	v_mfma_f32_32x32x16_bf16 v[82:97], v[138:141], v[150:153], v[82:97]
	ds_read_b64_tr_b16 v[150:151], v0 offset:0x5000
	ds_read_b64_tr_b16 v[152:153], v0 offset:0x5800
	s_add_i32 m0, s72, 0x8c00
	v_lshl_add_u64 v[248:249], v[246:247], 0, s[16:17]
	global_load_lds_dwordx4 v[248:249], off
	v_mfma_f32_32x32x16_bf16 v[82:97], v[134:137], v[154:157], v[82:97]
	ds_read_b64_tr_b16 v[154:155], v0 offset:0x6000
	ds_read_b64_tr_b16 v[156:157], v0 offset:0x6800
	v_mfma_f32_32x32x16_bf16 v[82:97], v[130:133], v[158:161], v[82:97]
	ds_read_b64_tr_b16 v[158:159], v0 offset:0x7000
	ds_read_b64_tr_b16 v[160:161], v0 offset:0x7800
	s_waitcnt lgkmcnt(8)
	s_add_i32 m0, s72, 0xcc00
	v_lshl_add_u64 v[250:251], v[246:247], 0, s[18:19]
	global_load_lds_dwordx4 v[250:251], off
	v_mfma_f32_32x32x16_bf16 v[66:81], v[142:145], v[184:187], v[66:81]
	ds_read_b64_tr_b16 v[184:185], v0 offset:0x4200
	ds_read_b64_tr_b16 v[186:187], v0 offset:0x4a00
	v_mfma_f32_32x32x16_bf16 v[66:81], v[138:141], v[188:191], v[66:81]
	ds_read_b64_tr_b16 v[188:189], v0 offset:0x5200
	ds_read_b64_tr_b16 v[190:191], v0 offset:0x5a00
	v_mfma_f32_32x32x16_bf16 v[66:81], v[134:137], v[192:195], v[66:81]
	ds_read_b64_tr_b16 v[192:193], v0 offset:0x6200
	ds_read_b64_tr_b16 v[194:195], v0 offset:0x6a00
	v_mfma_f32_32x32x16_bf16 v[66:81], v[130:133], v[196:199], v[66:81]
	ds_read_b64_tr_b16 v[196:197], v0 offset:0x7200
	ds_read_b64_tr_b16 v[198:199], v0 offset:0x7a00
	s_waitcnt lgkmcnt(8)
	v_mfma_f32_32x32x16_bf16 v[50:65], v[142:145], v[146:149], v[50:65]
	ds_read_b64_tr_b16 v[146:147], v0 offset:0x4400
	ds_read_b64_tr_b16 v[148:149], v0 offset:0x4c00
	v_mfma_f32_32x32x16_bf16 v[50:65], v[138:141], v[150:153], v[50:65]
	ds_read_b64_tr_b16 v[150:151], v0 offset:0x5400
	ds_read_b64_tr_b16 v[152:153], v0 offset:0x5c00
	v_mfma_f32_32x32x16_bf16 v[50:65], v[134:137], v[154:157], v[50:65]
	ds_read_b64_tr_b16 v[154:155], v0 offset:0x6400
	ds_read_b64_tr_b16 v[156:157], v0 offset:0x6c00
	v_mfma_f32_32x32x16_bf16 v[50:65], v[130:133], v[158:161], v[50:65]
	ds_read_b64_tr_b16 v[158:159], v0 offset:0x7400
	ds_read_b64_tr_b16 v[160:161], v0 offset:0x7c00
	s_waitcnt lgkmcnt(8)
	v_mfma_f32_32x32x16_bf16 v[34:49], v[142:145], v[184:187], v[34:49]
	ds_read_b64_tr_b16 v[184:185], v0 offset:0x4600
	ds_read_b64_tr_b16 v[186:187], v0 offset:0x4e00
	v_mfma_f32_32x32x16_bf16 v[34:49], v[138:141], v[188:191], v[34:49]
	ds_read_b64_tr_b16 v[188:189], v0 offset:0x5600
	ds_read_b64_tr_b16 v[190:191], v0 offset:0x5e00
	v_mfma_f32_32x32x16_bf16 v[34:49], v[134:137], v[192:195], v[34:49]
	ds_read_b64_tr_b16 v[192:193], v0 offset:0x6600
	ds_read_b64_tr_b16 v[194:195], v0 offset:0x6e00
	v_mfma_f32_32x32x16_bf16 v[34:49], v[130:133], v[196:199], v[34:49]
	ds_read_b64_tr_b16 v[196:197], v0 offset:0x7600
	ds_read_b64_tr_b16 v[198:199], v0 offset:0x7e00
	s_waitcnt lgkmcnt(8)
	v_mfma_f32_32x32x16_bf16 v[18:33], v[142:145], v[146:149], v[18:33]
	s_waitcnt lgkmcnt(0)
	v_mfma_f32_32x32x16_bf16 v[18:33], v[138:141], v[150:153], v[18:33]
	v_mfma_f32_32x32x16_bf16 v[18:33], v[134:137], v[154:157], v[18:33]
	v_mfma_f32_32x32x16_bf16 v[18:33], v[130:133], v[158:161], v[18:33]
	v_mfma_f32_32x32x16_bf16 v[2:17], v[142:145], v[184:187], v[2:17]
	s_waitcnt vmcnt(0)
	s_add_i32 s70, s70, 1
	s_waitcnt lgkmcnt(0)
	s_barrier
	s_add_u32 s48, s48, 0x4000
	s_addc_u32 s49, s49, 0
	v_mfma_f32_32x32x16_bf16 v[2:17], v[138:141], v[188:191], v[2:17]
	s_cmp_eq_u32 s48, 0x1fc000
	v_mfma_f32_32x32x16_bf16 v[2:17], v[134:137], v[192:195], v[2:17]
	v_mfma_f32_32x32x16_bf16 v[2:17], v[130:133], v[196:199], v[2:17]
	s_cbranch_scc1 .LBB0_503

; #define RS_BAR() do { asm volatile("s_waitcnt lgkmcnt(0)" ::: "memory"); __builtin_amdgcn_s_barrier(); asm volatile("" ::: "memory"); } while (0)
; #define KDMA(t, kb) do { _Pragma("unroll") for (int i = 0; i < 4; ++i) \
;       __builtin_amdgcn_global_load_lds((const unsigned*)(Kc + (long)(t) * 8192 + kdo[i]), (ATT_LAS unsigned*)(lds + RS_K + (kb) * 16384 + (pw * 4 + i) * 1024), 16, 0, 0); } while (0)
; #define VM0() asm volatile("s_waitcnt vmcnt(0)" ::: "memory")
; #define VM0() asm volatile("s_waitcnt vmcnt(0)" ::: "memory")
; template <class Epi>
; __device__ __forceinline__ void attn_rs_body(const bf16* __restrict__ Qb, const bf16* __restrict__ Kc, const bf16* __restrict__ V0c, const bf16* __restrict__ V1c, int NT, char* lds, const Epi& epi) {
;     ...
;   if (wid < 4) {
;     bf16x8 qr[8];
;     { const bf16* Ql = Qb + (long)(pw * 32 + r32) * 128 + hi * 8;
; #pragma unroll
;       for (int d0 = 0; d0 < 8; ++d0) qr[d0] = *reinterpret_cast<const bf16x8*>(Ql + d0 * 16); }
;     long kdo[4];
; #pragma unroll
;     for (int i = 0; i < 4; ++i) { const int r = 16 * pw + 4 * i + (lane >> 4), c = (lane & 15) ^ (r & 7); kdo[i] = (long)r * 128 + c * 8; }
;     ...
;     const int kfb = (int)(uintptr_t)(lds + RS_K) + r32 * 256, ksw = (r32 & 7) << 4, hi16 = hi * 16;
;     ...
;     float m_reg = -1e30f, l_reg = 0.f;
;     f32x16 pA0, pA1, pB0, pB1;
;     KDMA(0, 0); KDMA(1, 1); VM0();
;     RS_BAR();
;     QKT_PF(pA0, pA1, 0);
;     RS_BAR();
.LBB0_506:
	s_add_i32 s1, s0, s8
	s_add_i32 s4, s1, 32
	s_ashr_i32 s5, s4, 31
	s_lshl_b32 s48, s2, 5
	s_lshl_b64 s[4:5], s[4:5], 21
	s_add_u32 s46, s33, s4
	s_addc_u32 s47, s54, s5
	s_or_b32 s0, s0, s8
	s_ashr_i32 s1, s0, 31
	s_lshl_b64 s[0:1], s[0:1], 21
	s_add_u32 s0, s33, s0
	s_addc_u32 s1, s54, s1
	s_lshl_b32 s3, s3, 15
	s_add_u32 s0, s0, s3
	v_or_b32_e32 v0, s48, v178
	s_addc_u32 s1, s1, 0
	v_lshlrev_b32_e32 v0, 8, v0
	v_lshl_add_u64 v[2:3], s[0:1], 0, v[0:1]
	v_mov_b32_e32 v165, v1
	v_lshl_add_u64 v[2:3], v[2:3], 0, v[164:165]
	global_load_dwordx4 v[66:69], v[2:3], off
	global_load_dwordx4 v[70:73], v[2:3], off offset:32
	global_load_dwordx4 v[74:77], v[2:3], off offset:64
	global_load_dwordx4 v[78:81], v[2:3], off offset:96
	global_load_dwordx4 v[82:85], v[2:3], off offset:128
	global_load_dwordx4 v[86:89], v[2:3], off offset:160
	global_load_dwordx4 v[90:93], v[2:3], off offset:192
	global_load_dwordx4 v[94:97], v[2:3], off offset:224
	v_lshrrev_b32_e32 v0, 4, v180
	v_and_b32_e32 v2, 15, v181
	v_lshlrev_b32_e32 v4, 7, v0
	v_bitop3_b32 v3, v0, v181, 15 bitop3:0x78
	v_lshl_or_b32 v4, s2, 11, v4
	v_bitop3_b32 v0, v0, v2, 4 bitop3:0x36
	v_lshl_or_b32 v98, v3, 3, v4
	v_lshl_or_b32 v118, v0, 3, v4
	v_lshlrev_b32_e32 v2, 1, v118
	v_lshlrev_b32_e32 v0, 1, v98
	v_mov_b32_e32 v3, v1
	s_mov_b32 m0, s64
	v_lshl_add_u64 v[4:5], s[46:47], 0, v[0:1]
	v_lshl_add_u64 v[6:7], s[46:47], 0, v[2:3]
	s_add_i32 s2, s64, 0x400
	s_add_i32 s3, s64, 0x800
	s_add_i32 s66, s64, 0xc00
	global_load_lds_dwordx4 v[4:5], off
	v_lshl_add_u64 v[8:9], v[6:7], 0, s[40:41]
	s_mov_b32 m0, s2
	s_cmp_lg_u32 0, -1
	global_load_lds_dwordx4 v[8:9], off
	v_lshl_add_u64 v[4:5], v[4:5], 0, s[42:43]
	s_mov_b32 m0, s3
	s_cselect_b32 s4, 0, 0
	s_add_u32 s0, s46, 0x4000
	global_load_lds_dwordx4 v[4:5], off
	v_lshl_add_u64 v[4:5], v[6:7], 0, s[44:45]
	s_mov_b32 m0, s66
	s_addc_u32 s1, s47, 0
	s_add_i32 s67, s64, 0x4000
	global_load_lds_dwordx4 v[4:5], off
	v_lshl_add_u64 v[4:5], s[0:1], 0, v[0:1]
	s_mov_b32 m0, s67
	s_add_i32 s68, s64, 0x4400
	global_load_lds_dwordx4 v[4:5], off
	v_or_b32_e32 v4, 0x400, v2
	v_mov_b32_e32 v5, v1
	v_lshl_add_u64 v[4:5], s[0:1], 0, v[4:5]
	s_mov_b32 m0, s68
	v_or_b32_e32 v0, 0x800, v0
	s_add_i32 s69, s64, 0x4800
	global_load_lds_dwordx4 v[4:5], off
	v_lshl_add_u64 v[4:5], s[0:1], 0, v[0:1]
	s_mov_b32 m0, s69
	v_or_b32_e32 v0, 0xc00, v2
	s_add_i32 s70, s64, 0x4c00
	global_load_lds_dwordx4 v[4:5], off
	v_lshl_add_u64 v[2:3], s[0:1], 0, v[0:1]
	s_mov_b32 m0, s70
	v_lshlrev_b32_e32 v99, 8, v178
	global_load_lds_dwordx4 v[2:3], off
	v_lshlrev_b32_e32 v10, 4, v181
	v_and_b32_e32 v107, 0x70, v10
	v_add_u32_e32 v108, s4, v99
	s_waitcnt vmcnt(0)
	v_bitop3_b32 v0, v164, v10, s57 bitop3:0x78
	s_waitcnt lgkmcnt(0)
	s_barrier
	v_add_u32_e32 v100, v0, v108
	ds_read_b128 v[2:5], v100
	ds_read_b128 v[6:9], v100 offset:8192
	v_bitop3_b32 v109, v164, v107, 32 bitop3:0x36
	v_bitop3_b32 v110, v164, v107, 64 bitop3:0x36
	v_bitop3_b32 v111, v164, v107, s58 bitop3:0x36
	v_add_u32_e32 v101, v109, v108
	ds_read_b128 v[34:37], v101
	ds_read_b128 v[38:41], v101 offset:8192
	v_add_u32_e32 v102, v110, v108
	ds_read_b128 v[42:45], v102
	ds_read_b128 v[46:49], v102 offset:8192
	v_add_u32_e32 v103, v111, v108
	ds_read_b128 v[50:53], v103
	ds_read_b128 v[54:57], v103 offset:8192
	s_waitcnt lgkmcnt(6)
	s_movk_i32 s0, 0x80
	s_waitcnt vmcnt(0)
	v_mfma_f32_32x32x16_bf16 v[18:33], v[2:5], v[66:69], 0
	v_bitop3_b32 v112, v164, v107, s0 bitop3:0x36
	v_add_u32_e32 v104, v112, v108
	ds_read_b128 v[58:61], v104
	ds_read_b128 v[62:65], v104 offset:8192
	s_waitcnt lgkmcnt(6)
	v_bitop3_b32 v114, v164, v107, s59 bitop3:0x36
	v_add_u32_e32 v105, v114, v108
	v_mfma_f32_32x32x16_bf16 v[2:17], v[6:9], v[66:69], 0
	s_movk_i32 s0, 0xc0
	v_bitop3_b32 v115, v164, v107, s0 bitop3:0x36
	v_add_u32_e32 v106, v115, v108
	v_bitop3_b32 v116, v164, v107, s60 bitop3:0x36
	v_add_u32_e32 v107, v116, v108
	s_addk_i32 s4, 0x4000
	s_mov_b32 s71, 0
	v_mfma_f32_32x32x16_bf16 v[18:33], v[34:37], v[70:73], v[18:33]
	ds_read_b128 v[34:37], v105
	v_cmp_gt_u32_e64 s[0:1], 32, v180
	v_lshl_add_u32 v117, v178, 2, s65
	v_mov_b32_e32 v121, 0xf149f2ca
	s_movk_i32 s72, 0x6000
	v_mfma_f32_32x32x16_bf16 v[2:17], v[38:41], v[70:73], v[2:17]
	ds_read_b128 v[38:41], v105 offset:8192
	s_waitcnt lgkmcnt(6)
	s_nop 0
	v_mfma_f32_32x32x16_bf16 v[18:33], v[42:45], v[74:77], v[18:33]
	ds_read_b128 v[42:45], v106
	v_mfma_f32_32x32x16_bf16 v[2:17], v[46:49], v[74:77], v[2:17]
	ds_read_b128 v[46:49], v106 offset:8192
	s_waitcnt lgkmcnt(6)
	s_nop 0
	v_mfma_f32_32x32x16_bf16 v[18:33], v[50:53], v[78:81], v[18:33]
	ds_read_b128 v[50:53], v107
	v_mfma_f32_32x32x16_bf16 v[2:17], v[54:57], v[78:81], v[2:17]
	ds_read_b128 v[54:57], v107 offset:8192
	s_waitcnt lgkmcnt(6)
	s_waitcnt lgkmcnt(4)
	s_waitcnt lgkmcnt(2)
	s_nop 0
	s_waitcnt lgkmcnt(0)
	s_waitcnt lgkmcnt(0)
	v_mfma_f32_32x32x16_bf16 v[18:33], v[58:61], v[82:85], v[18:33]
	s_barrier
	v_mfma_f32_32x32x16_bf16 v[2:17], v[62:65], v[82:85], v[2:17]
	v_mfma_f32_32x32x16_bf16 v[18:33], v[34:37], v[86:89], v[18:33]
	v_add_u32_e32 v34, s4, v99
	v_add_u32_e32 v108, v0, v34
	v_add_u32_e32 v109, v109, v34
	v_add_u32_e32 v110, v110, v34
	v_add_u32_e32 v111, v111, v34
	v_add_u32_e32 v113, v112, v34
	v_add_u32_e32 v114, v114, v34
	v_mfma_f32_32x32x16_bf16 v[2:17], v[38:41], v[86:89], v[2:17]
	v_add_u32_e32 v115, v115, v34
	v_add_u32_e32 v116, v116, v34
	v_cmp_eq_u32_e64 s[4:5], 0, v180
	v_mov_b32_e32 v112, 0
	v_lshlrev_b32_e32 v0, 1, v98
	v_lshlrev_b32_e32 v98, 1, v118
	v_mfma_f32_32x32x16_bf16 v[18:33], v[42:45], v[90:93], v[18:33]
	v_mfma_f32_32x32x16_bf16 v[2:17], v[46:49], v[90:93], v[2:17]
	v_mfma_f32_32x32x16_bf16 v[18:33], v[50:53], v[94:97], v[18:33]
	v_mfma_f32_32x32x16_bf16 v[2:17], v[54:57], v[94:97], v[2:17]
	v_add_u32_e32 v236, 0x400, v98
	v_add_u32_e32 v237, 0x800, v0
	v_add_u32_e32 v238, 0xc00, v98
	s_nop 7
	s_nop 7
	s_branch .LBB0_508

; __device__ __forceinline__ void partialSM(f32x16& p0, f32x16& p1, float& m_reg, float& mn, float& alpha) {
;   constexpr float C = SCALE * L2E;
;   float pmax = p0[0];
; #pragma unroll
;   for (int r = 1; r < 16; ++r) pmax = fmaxf(pmax, p0[r]);
; #pragma unroll
;   for (int r = 0; r < 16; ++r) pmax = fmaxf(pmax, p1[r]);
;   { auto rr = __builtin_amdgcn_permlane32_swap(__float_as_uint(pmax), __float_as_uint(pmax), false, false);
;     pmax = fmaxf(__uint_as_float(rr[0]), __uint_as_float(rr[1])); }
;   if (__builtin_expect(__all(pmax - m_reg <= THR / SCALE), 1)) { mn = m_reg; alpha = 1.f; }
;   else { mn = fmaxf(m_reg, pmax); alpha = __builtin_amdgcn_exp2f((m_reg - mn) * C); m_reg = mn; }
;   float mnC = -mn * C;
; #pragma unroll
;   for (int r = 0; r < 16; ++r) p0[r] = fmaf(p0[r], C, mnC);
; #pragma unroll
;   for (int r = 0; r < 16; ++r) p1[r] = fmaf(p1[r], C, mnC);
; #pragma unroll
;   for (int r = 0; r < 16; ++r) p0[r] = __builtin_amdgcn_exp2f(p0[r]);
; }
.LBB0_508:
	s_cmpk_gt_u32 s71, 0x7d
	s_cselect_b64 s[48:49], -1, 0
	s_add_i32 s8, s72, 0xffffe000
	s_cmpk_lt_u32 s71, 0x7e
	s_cselect_b32 s8, s8, 0xfe000
	s_lshl_b64 s[84:85], s[8:9], 1
	s_add_u32 s84, s46, s84
	s_addc_u32 s85, s47, s85
	ds_read_b128 v[200:203], v108
	ds_read_b128 v[204:207], v108 offset:8192
	ds_read_b128 v[208:211], v109
	ds_read_b128 v[212:215], v109 offset:8192
	ds_read_b128 v[216:219], v110
	ds_read_b128 v[220:223], v110 offset:8192
	ds_read_b128 v[224:227], v111
	ds_read_b128 v[228:231], v111 offset:8192
	v_max_f32_e32 v99, v19, v19
	v_max_f32_e32 v118, v18, v18
	v_max_f32_e32 v99, v118, v99
	v_max3_f32 v99, v99, v20, v21
	v_max3_f32 v99, v99, v22, v23
	v_max3_f32 v99, v99, v24, v25
	v_max3_f32 v99, v99, v26, v27
	v_max3_f32 v99, v99, v28, v29
	v_max3_f32 v99, v99, v30, v31
	v_max3_f32 v99, v99, v32, v33
	s_waitcnt lgkmcnt(6)
	v_mfma_f32_32x32x16_bf16 v[50:65], v[200:203], v[66:69], 0
	v_max3_f32 v99, v99, v2, v3
	v_max3_f32 v99, v99, v4, v5
	v_max3_f32 v99, v99, v6, v7
	v_max3_f32 v99, v99, v8, v9
	v_max3_f32 v99, v99, v10, v11
	v_max3_f32 v99, v99, v12, v13
	v_max3_f32 v99, v99, v14, v15
	v_max3_f32 v99, v99, v16, v17
	v_mov_b32_e32 v118, v99
	v_mfma_f32_32x32x16_bf16 v[34:49], v[204:207], v[66:69], 0
	s_mov_b32 m0, s64
	ds_read_b128 v[200:203], v113
	ds_read_b128 v[204:207], v113 offset:8192
	global_load_lds_dwordx4 v0, s[84:85]
	s_nop 1
	v_permlane32_swap_b32_e32 v99, v118
	v_max_f32_e32 v118, v118, v118
	v_max_f32_e32 v99, v99, v99
	v_max_f32_e32 v99, v99, v118
	v_sub_f32_e32 v118, v99, v121
	v_cmp_ge_f32_e32 vcc, s61, v118
	v_max_f32_e32 v119, v121, v121
	s_cmp_eq_u64 vcc, exec
	v_max_f32_e32 v99, v119, v99
	s_cselect_b64 vcc, -1, 0
	s_waitcnt lgkmcnt(6)
	v_mfma_f32_32x32x16_bf16 v[50:65], v[208:211], v[70:73], v[50:65]
	v_sub_f32_e32 v119, v121, v99
	v_cndmask_b32_e32 v121, v99, v121, vcc
	v_mul_f32_e32 v99, 0xbe0293ee, v121
	v_fmamk_f32 v18, v18, 0x3e0293ee, v99
	v_fmamk_f32 v19, v19, 0x3e0293ee, v99
	v_fmamk_f32 v20, v20, 0x3e0293ee, v99
	v_fmamk_f32 v21, v21, 0x3e0293ee, v99
	v_fmamk_f32 v22, v22, 0x3e0293ee, v99
	v_mfma_f32_32x32x16_bf16 v[34:49], v[212:215], v[70:73], v[34:49]
	s_mov_b32 m0, s2
	ds_read_b128 v[208:211], v114
	ds_read_b128 v[212:215], v114 offset:8192
	global_load_lds_dwordx4 v236, s[84:85]
	v_fmamk_f32 v23, v23, 0x3e0293ee, v99
	v_fmamk_f32 v24, v24, 0x3e0293ee, v99
	v_fmamk_f32 v25, v25, 0x3e0293ee, v99
	v_fmamk_f32 v26, v26, 0x3e0293ee, v99
	v_fmamk_f32 v27, v27, 0x3e0293ee, v99
	v_fmamk_f32 v28, v28, 0x3e0293ee, v99
	v_fmamk_f32 v29, v29, 0x3e0293ee, v99
	v_fmamk_f32 v30, v30, 0x3e0293ee, v99
	v_fmamk_f32 v31, v31, 0x3e0293ee, v99
	s_waitcnt lgkmcnt(6)
	v_mfma_f32_32x32x16_bf16 v[50:65], v[216:219], v[74:77], v[50:65]
	v_fmamk_f32 v32, v32, 0x3e0293ee, v99
	v_fmamk_f32 v33, v33, 0x3e0293ee, v99
	v_fmamk_f32 v2, v2, 0x3e0293ee, v99
	v_fmamk_f32 v3, v3, 0x3e0293ee, v99
	v_fmamk_f32 v4, v4, 0x3e0293ee, v99
	v_fmamk_f32 v5, v5, 0x3e0293ee, v99
	v_fmamk_f32 v6, v6, 0x3e0293ee, v99
	v_fmamk_f32 v7, v7, 0x3e0293ee, v99
	v_fmamk_f32 v8, v8, 0x3e0293ee, v99
	v_mfma_f32_32x32x16_bf16 v[34:49], v[220:223], v[74:77], v[34:49]
	s_mov_b32 m0, s3
	ds_read_b128 v[216:219], v115
	ds_read_b128 v[220:223], v115 offset:8192
	global_load_lds_dwordx4 v237, s[84:85]
	v_fmamk_f32 v9, v9, 0x3e0293ee, v99
	v_fmamk_f32 v10, v10, 0x3e0293ee, v99
	v_fmamk_f32 v11, v11, 0x3e0293ee, v99
	v_fmamk_f32 v12, v12, 0x3e0293ee, v99
	v_fmamk_f32 v13, v13, 0x3e0293ee, v99
	v_fmamk_f32 v14, v14, 0x3e0293ee, v99
	v_fmamk_f32 v15, v15, 0x3e0293ee, v99
	v_fmamk_f32 v16, v16, 0x3e0293ee, v99
	v_fmac_f32_e32 v99, 0x3e0293ee, v17
	v_exp_f32_e32 v17, v18
	s_waitcnt lgkmcnt(6)
	v_mfma_f32_32x32x16_bf16 v[50:65], v[224:227], v[78:81], v[50:65]
	v_exp_f32_e32 v18, v19
	v_exp_f32_e32 v19, v20
	v_exp_f32_e32 v20, v21
	v_exp_f32_e32 v21, v22
	v_exp_f32_e32 v22, v23
	v_exp_f32_e32 v23, v24
	v_exp_f32_e32 v24, v25
	v_exp_f32_e32 v25, v26
	v_exp_f32_e32 v26, v27
	v_mfma_f32_32x32x16_bf16 v[34:49], v[228:231], v[78:81], v[34:49]
	s_mov_b32 m0, s66
	ds_read_b128 v[224:227], v116
	ds_read_b128 v[228:231], v116 offset:8192
	global_load_lds_dwordx4 v238, s[84:85]
	v_exp_f32_e32 v27, v28
	v_exp_f32_e32 v28, v29
	v_exp_f32_e32 v29, v30
	v_exp_f32_e32 v30, v31
	v_exp_f32_e32 v31, v32
	v_exp_f32_e32 v32, v33
	v_exp_f32_e32 v33, v2
	v_add_f32_e32 v2, 0, v17
	v_add_f32_e32 v2, v18, v2
	s_waitcnt lgkmcnt(6)
	v_mfma_f32_32x32x16_bf16 v[50:65], v[200:203], v[82:85], v[50:65]
	v_add_f32_e32 v2, v19, v2
	v_add_f32_e32 v2, v20, v2
	v_add_f32_e32 v2, v21, v2
	v_add_f32_e32 v2, v22, v2
	v_add_f32_e32 v2, v23, v2
	v_add_f32_e32 v2, v24, v2
	v_add_f32_e32 v2, v25, v2
	v_add_f32_e32 v2, v26, v2
	v_add_f32_e32 v2, v27, v2
	v_add_f32_e32 v2, v28, v2
	v_mfma_f32_32x32x16_bf16 v[34:49], v[204:207], v[82:85], v[34:49]
	v_add_f32_e32 v2, v29, v2
	v_exp_f32_e32 v122, v3
	v_add_f32_e32 v2, v30, v2
	v_exp_f32_e32 v123, v4
	v_add_f32_e32 v2, v31, v2
	v_exp_f32_e32 v124, v5
	v_add_f32_e32 v2, v32, v2
	v_exp_f32_e32 v125, v6
	v_add_f32_e32 v2, v33, v2
	s_waitcnt lgkmcnt(4)
	v_mfma_f32_32x32x16_bf16 v[50:65], v[208:211], v[86:89], v[50:65]
	v_exp_f32_e32 v126, v7
	v_add_f32_e32 v2, v122, v2
	v_exp_f32_e32 v127, v8
	v_add_f32_e32 v2, v123, v2
	v_exp_f32_e32 v128, v9
	v_add_f32_e32 v2, v124, v2
	v_exp_f32_e32 v129, v10
	v_add_f32_e32 v2, v125, v2
	v_exp_f32_e32 v130, v11
	v_mfma_f32_32x32x16_bf16 v[34:49], v[212:215], v[86:89], v[34:49]
	v_add_f32_e32 v2, v126, v2
	v_exp_f32_e32 v131, v12
	v_add_f32_e32 v2, v127, v2
	v_exp_f32_e32 v132, v13
	v_add_f32_e32 v2, v128, v2
	v_mul_f32_e32 v119, 0x3e0293ee, v119
	v_exp_f32_e32 v133, v14
	v_add_f32_e32 v2, v129, v2
	v_exp_f32_e32 v119, v119
	v_exp_f32_e32 v134, v15
	s_waitcnt lgkmcnt(2)
; __device__ __forceinline__ void finishSM(f32x16& p0, f32x16& p1, float alpha, float& l_reg, bf16x8& pa0, bf16x8& pa1, bf16x8& pa2, bf16x8& pa3) {
; #pragma unroll
;   for (int r = 0; r < 16; ++r) p1[r] = __builtin_amdgcn_exp2f(p1[r]);
;   float ps = 0;
; #pragma unroll
;   for (int r = 0; r < 16; ++r) ps += p0[r];
; #pragma unroll
;   for (int r = 0; r < 16; ++r) ps += p1[r];
;   { auto rr = __builtin_amdgcn_permlane32_swap(__float_as_uint(ps), __float_as_uint(ps), false, false);
;     ps = __uint_as_float(rr[0]) + __uint_as_float(rr[1]); }
;   l_reg = l_reg * alpha + ps;
;     ...
;   PK4(p0, 0, pa0); PK4(p0, 8, pa1); PK4(p1, 0, pa2); PK4(p1, 8, pa3);
;     ...
; }
	v_mfma_f32_32x32x16_bf16 v[50:65], v[216:219], v[90:93], v[50:65]
	v_add_f32_e32 v2, v130, v2
	v_exp_f32_e32 v135, v16
	v_add_f32_e32 v2, v131, v2
	v_exp_f32_e32 v99, v99
	v_add_f32_e32 v2, v132, v2
	v_add_f32_e32 v2, v133, v2
	v_cndmask_b32_e64 v118, v119, 1.0, vcc
	v_add_f32_e32 v2, v134, v2
	v_add_f32_e32 v2, v135, v2
	v_mfma_f32_32x32x16_bf16 v[34:49], v[220:223], v[90:93], v[34:49]
	v_cmp_gt_f32_e32 vcc, 1.0, v118
	v_add_f32_e32 v119, v99, v2
	s_cmp_lg_u64 vcc, 0
	v_mov_b32_e32 v120, v119
	v_cvt_pk_bf16_f32 v2, v17, v18
	v_cvt_pk_bf16_f32 v3, v19, v20
	v_cvt_pk_bf16_f32 v4, v21, v22
	v_cvt_pk_bf16_f32 v5, v23, v24
	s_cselect_b64 s[50:51], -1, 0
	s_waitcnt lgkmcnt(0)
	v_mfma_f32_32x32x16_bf16 v[50:65], v[224:227], v[94:97], v[50:65]
	s_nop 0
	v_permlane32_swap_b32_e32 v119, v120
	v_permlane32_swap_b32_e32 v2, v4
	v_permlane32_swap_b32_e32 v3, v5
	v_cvt_pk_bf16_f32 v6, v25, v26
	v_cvt_pk_bf16_f32 v7, v27, v28
	v_cvt_pk_bf16_f32 v8, v29, v30
	v_cvt_pk_bf16_f32 v9, v31, v32
	v_cvt_pk_bf16_f32 v10, v33, v122
	v_cvt_pk_bf16_f32 v11, v123, v124
	v_mfma_f32_32x32x16_bf16 v[34:49], v[228:231], v[94:97], v[34:49]
	v_cvt_pk_bf16_f32 v12, v125, v126
	v_cvt_pk_bf16_f32 v13, v127, v128
	v_cvt_pk_bf16_f32 v14, v129, v130
	v_cvt_pk_bf16_f32 v15, v131, v132
	v_cvt_pk_bf16_f32 v16, v133, v134
	v_cvt_pk_bf16_f32 v17, v135, v99
	s_and_b64 s[74:75], s[50:51], s[0:1]
	v_permlane32_swap_b32_e32 v6, v8
	v_permlane32_swap_b32_e32 v7, v9
	v_permlane32_swap_b32_e32 v10, v12
	v_permlane32_swap_b32_e32 v11, v13
	v_permlane32_swap_b32_e32 v14, v16
	v_permlane32_swap_b32_e32 v15, v17
	ds_write_b128 v179, v[2:5]
	ds_write_b128 v179, v[6:9] offset:1024
	ds_write_b128 v179, v[10:13] offset:2048
	ds_write_b128 v179, v[14:17] offset:3072
	s_and_saveexec_b64 s[52:53], s[74:75]
	ds_write_b32 v117, v118
	s_or_b64 exec, exec, s[52:53]
	s_and_saveexec_b64 s[52:53], s[4:5]
	v_cndmask_b32_e64 v2, 0, 1.0, s[50:51]
	v_mov_b32_e32 v3, s65
	ds_write_b32 v3, v2 offset:128
	s_or_b64 exec, exec, s[52:53]
	s_waitcnt vmcnt(0)
	s_waitcnt lgkmcnt(0)
	s_barrier
	s_cmpk_lt_u32 s71, 0x7d
	s_cselect_b32 s8, s72, 0xfe000
	s_lshl_b64 s[84:85], s[8:9], 1
	s_add_u32 s84, s46, s84
	s_addc_u32 s85, s47, s85
	ds_read_b128 v[200:203], v100
	ds_read_b128 v[204:207], v100 offset:8192
	ds_read_b128 v[208:211], v101
	ds_read_b128 v[212:215], v101 offset:8192
	ds_read_b128 v[216:219], v102
	ds_read_b128 v[220:223], v102 offset:8192
	ds_read_b128 v[224:227], v103
	ds_read_b128 v[228:231], v103 offset:8192
	v_max_f32_e32 v99, v51, v51
	v_max_f32_e32 v122, v50, v50
	v_max_f32_e32 v99, v122, v99
	v_max3_f32 v99, v99, v52, v53
	v_max3_f32 v99, v99, v54, v55
	v_max3_f32 v99, v99, v56, v57
	v_max3_f32 v99, v99, v58, v59
	v_max3_f32 v99, v99, v60, v61
	v_max3_f32 v99, v99, v62, v63
	v_max3_f32 v99, v99, v64, v65
	s_waitcnt lgkmcnt(6)
	v_mfma_f32_32x32x16_bf16 v[18:33], v[200:203], v[66:69], 0
	v_max3_f32 v99, v99, v34, v35
	v_max3_f32 v99, v99, v36, v37
	v_max3_f32 v99, v99, v38, v39
	v_max3_f32 v99, v99, v40, v41
	v_max3_f32 v99, v99, v42, v43
	v_max3_f32 v99, v99, v44, v45
	v_max3_f32 v99, v99, v46, v47
	v_max3_f32 v99, v99, v48, v49
	v_mov_b32_e32 v122, v99
	v_mfma_f32_32x32x16_bf16 v[2:17], v[204:207], v[66:69], 0
	s_mov_b32 m0, s67
	ds_read_b128 v[200:203], v104
	ds_read_b128 v[204:207], v104 offset:8192
	global_load_lds_dwordx4 v0, s[84:85]
	s_nop 1
	v_permlane32_swap_b32_e32 v99, v122
	v_max_f32_e32 v122, v122, v122
	v_max_f32_e32 v99, v99, v99
	v_max_f32_e32 v99, v99, v122
	v_sub_f32_e32 v122, v99, v121
	v_cmp_ge_f32_e32 vcc, s61, v122
	v_max_f32_e32 v123, v121, v121
	s_cmp_eq_u64 vcc, exec
	v_max_f32_e32 v123, v123, v99
	s_cselect_b64 vcc, -1, 0
	s_waitcnt lgkmcnt(6)
	v_mfma_f32_32x32x16_bf16 v[18:33], v[208:211], v[70:73], v[18:33]
	v_sub_f32_e32 v99, v121, v123
	v_cndmask_b32_e32 v121, v123, v121, vcc
	v_mul_f32_e32 v122, 0xbe0293ee, v121
	v_fmamk_f32 v50, v50, 0x3e0293ee, v122
	v_fmamk_f32 v51, v51, 0x3e0293ee, v122
	v_fmamk_f32 v52, v52, 0x3e0293ee, v122
	v_fmamk_f32 v53, v53, 0x3e0293ee, v122
	v_fmamk_f32 v54, v54, 0x3e0293ee, v122
	v_mfma_f32_32x32x16_bf16 v[2:17], v[212:215], v[70:73], v[2:17]
	s_mov_b32 m0, s68
	ds_read_b128 v[208:211], v105
	ds_read_b128 v[212:215], v105 offset:8192
	global_load_lds_dwordx4 v236, s[84:85]
	v_fmamk_f32 v55, v55, 0x3e0293ee, v122
	v_fmamk_f32 v56, v56, 0x3e0293ee, v122
	v_fmamk_f32 v57, v57, 0x3e0293ee, v122
	v_fmamk_f32 v58, v58, 0x3e0293ee, v122
	v_fmamk_f32 v59, v59, 0x3e0293ee, v122
	v_fmamk_f32 v60, v60, 0x3e0293ee, v122
	v_fmamk_f32 v61, v61, 0x3e0293ee, v122
	v_fmamk_f32 v62, v62, 0x3e0293ee, v122
	v_fmamk_f32 v63, v63, 0x3e0293ee, v122
	s_waitcnt lgkmcnt(6)
; __device__ __forceinline__ void finishSM(f32x16& p0, f32x16& p1, float alpha, float& l_reg, bf16x8& pa0, bf16x8& pa1, bf16x8& pa2, bf16x8& pa3) {
; #pragma unroll
;   for (int r = 0; r < 16; ++r) p1[r] = __builtin_amdgcn_exp2f(p1[r]);
;   float ps = 0;
; #pragma unroll
;   for (int r = 0; r < 16; ++r) ps += p0[r];
; #pragma unroll
;   for (int r = 0; r < 16; ++r) ps += p1[r];
;   { auto rr = __builtin_amdgcn_permlane32_swap(__float_as_uint(ps), __float_as_uint(ps), false, false);
;     ps = __uint_as_float(rr[0]) + __uint_as_float(rr[1]); }
;   l_reg = l_reg * alpha + ps;
;     ...
;   PK4(p0, 0, pa0); PK4(p0, 8, pa1); PK4(p1, 0, pa2); PK4(p1, 8, pa3);
;     ...
; }
; template <class Epi>
; __device__ __forceinline__ void attn_rs_body(const bf16* __restrict__ Qb, const bf16* __restrict__ Kc, const bf16* __restrict__ V0c, const bf16* __restrict__ V1c, int NT, char* lds, const Epi& epi) {
;     ...
;     for (int j = 0; j < NT; j += 2) { RS_STEP(j, 0, pA0, pA1, pB0, pB1); RS_STEP(j + 1, 1, pB0, pB1, pA0, pA1); }
	v_mfma_f32_32x32x16_bf16 v[18:33], v[216:219], v[74:77], v[18:33]
	v_fmamk_f32 v64, v64, 0x3e0293ee, v122
	v_fmamk_f32 v65, v65, 0x3e0293ee, v122
	v_fmamk_f32 v34, v34, 0x3e0293ee, v122
	v_fmamk_f32 v35, v35, 0x3e0293ee, v122
	v_fmamk_f32 v36, v36, 0x3e0293ee, v122
	v_fmamk_f32 v37, v37, 0x3e0293ee, v122
	v_fmamk_f32 v38, v38, 0x3e0293ee, v122
	v_fmamk_f32 v39, v39, 0x3e0293ee, v122
	v_fmamk_f32 v40, v40, 0x3e0293ee, v122
	v_mfma_f32_32x32x16_bf16 v[2:17], v[220:223], v[74:77], v[2:17]
	s_mov_b32 m0, s69
	ds_read_b128 v[216:219], v106
	ds_read_b128 v[220:223], v106 offset:8192
	global_load_lds_dwordx4 v237, s[84:85]
	v_fmamk_f32 v41, v41, 0x3e0293ee, v122
	v_fmamk_f32 v42, v42, 0x3e0293ee, v122
	v_fmamk_f32 v43, v43, 0x3e0293ee, v122
	v_fmamk_f32 v44, v44, 0x3e0293ee, v122
	v_fmamk_f32 v45, v45, 0x3e0293ee, v122
	v_fmamk_f32 v46, v46, 0x3e0293ee, v122
	v_fmamk_f32 v47, v47, 0x3e0293ee, v122
	v_fmamk_f32 v48, v48, 0x3e0293ee, v122
	v_fmac_f32_e32 v122, 0x3e0293ee, v49
	v_exp_f32_e32 v49, v50
	s_waitcnt lgkmcnt(6)
	v_mfma_f32_32x32x16_bf16 v[18:33], v[224:227], v[78:81], v[18:33]
	v_exp_f32_e32 v50, v51
	v_exp_f32_e32 v51, v52
	v_exp_f32_e32 v52, v53
	v_exp_f32_e32 v53, v54
	v_exp_f32_e32 v54, v55
	v_exp_f32_e32 v55, v56
	v_exp_f32_e32 v56, v57
	v_exp_f32_e32 v57, v58
	v_exp_f32_e32 v58, v59
	v_mfma_f32_32x32x16_bf16 v[2:17], v[228:231], v[78:81], v[2:17]
	s_mov_b32 m0, s70
	ds_read_b128 v[224:227], v107
	ds_read_b128 v[228:231], v107 offset:8192
	global_load_lds_dwordx4 v238, s[84:85]
	v_exp_f32_e32 v59, v60
	v_exp_f32_e32 v60, v61
	v_exp_f32_e32 v61, v62
	v_exp_f32_e32 v62, v63
	v_exp_f32_e32 v63, v64
	v_exp_f32_e32 v64, v65
	v_exp_f32_e32 v65, v34
	v_add_f32_e32 v34, 0, v49
	v_add_f32_e32 v34, v50, v34
	s_waitcnt lgkmcnt(6)
	v_mfma_f32_32x32x16_bf16 v[18:33], v[200:203], v[82:85], v[18:33]
	v_add_f32_e32 v34, v51, v34
	v_add_f32_e32 v34, v52, v34
	v_add_f32_e32 v34, v53, v34
	v_add_f32_e32 v34, v54, v34
	v_add_f32_e32 v34, v55, v34
	v_add_f32_e32 v34, v56, v34
	v_add_f32_e32 v34, v57, v34
	v_add_f32_e32 v34, v58, v34
	v_add_f32_e32 v34, v59, v34
	v_add_f32_e32 v34, v60, v34
	v_mfma_f32_32x32x16_bf16 v[2:17], v[204:207], v[82:85], v[2:17]
	v_add_f32_e32 v34, v61, v34
	v_exp_f32_e32 v123, v35
	v_add_f32_e32 v34, v62, v34
	v_exp_f32_e32 v124, v36
	v_add_f32_e32 v34, v63, v34
	v_exp_f32_e32 v125, v37
	v_add_f32_e32 v34, v64, v34
	v_exp_f32_e32 v126, v38
	v_add_f32_e32 v34, v65, v34
	s_waitcnt lgkmcnt(4)
	v_mfma_f32_32x32x16_bf16 v[18:33], v[208:211], v[86:89], v[18:33]
	v_exp_f32_e32 v127, v39
	v_add_f32_e32 v34, v123, v34
	v_exp_f32_e32 v128, v40
	v_add_f32_e32 v34, v124, v34
	v_exp_f32_e32 v129, v41
	v_add_f32_e32 v34, v125, v34
	v_exp_f32_e32 v130, v42
	v_add_f32_e32 v34, v126, v34
	v_exp_f32_e32 v131, v43
	v_mfma_f32_32x32x16_bf16 v[2:17], v[212:215], v[86:89], v[2:17]
	v_add_f32_e32 v34, v127, v34
	v_exp_f32_e32 v132, v44
	v_add_f32_e32 v34, v128, v34
	v_exp_f32_e32 v133, v45
	v_add_f32_e32 v34, v129, v34
	v_mul_f32_e32 v99, 0x3e0293ee, v99
	v_exp_f32_e32 v134, v46
	v_add_f32_e32 v34, v130, v34
	v_exp_f32_e32 v99, v99
	v_exp_f32_e32 v135, v47
	s_waitcnt lgkmcnt(2)
	v_mfma_f32_32x32x16_bf16 v[18:33], v[216:219], v[90:93], v[18:33]
	v_add_f32_e32 v34, v131, v34
	v_exp_f32_e32 v136, v48
	v_add_f32_e32 v34, v132, v34
	v_exp_f32_e32 v122, v122
	v_add_f32_e32 v34, v133, v34
	v_add_f32_e32 v34, v134, v34
	v_cndmask_b32_e64 v99, v99, 1.0, vcc
	v_add_f32_e32 v34, v135, v34
	v_add_f32_e32 v34, v136, v34
	v_mfma_f32_32x32x16_bf16 v[2:17], v[220:223], v[90:93], v[2:17]
	v_cmp_gt_f32_e32 vcc, 1.0, v99
	v_add_f32_e32 v34, v122, v34
	s_cmp_lg_u64 vcc, 0
	v_mov_b32_e32 v35, v34
	v_cvt_pk_bf16_f32 v36, v49, v50
	v_cvt_pk_bf16_f32 v37, v51, v52
	v_cvt_pk_bf16_f32 v38, v53, v54
	v_cvt_pk_bf16_f32 v39, v55, v56
	s_cselect_b64 s[50:51], -1, 0
	s_waitcnt lgkmcnt(0)
	v_mfma_f32_32x32x16_bf16 v[18:33], v[224:227], v[94:97], v[18:33]
	s_nop 0
	v_permlane32_swap_b32_e32 v34, v35
	v_permlane32_swap_b32_e32 v36, v38
	v_permlane32_swap_b32_e32 v37, v39
	v_cvt_pk_bf16_f32 v40, v57, v58
	v_cvt_pk_bf16_f32 v41, v59, v60
	v_cvt_pk_bf16_f32 v42, v61, v62
	v_cvt_pk_bf16_f32 v43, v63, v64
	v_cvt_pk_bf16_f32 v44, v65, v123
	v_cvt_pk_bf16_f32 v45, v124, v125
	v_mfma_f32_32x32x16_bf16 v[2:17], v[228:231], v[94:97], v[2:17]
	v_cvt_pk_bf16_f32 v46, v126, v127
	v_cvt_pk_bf16_f32 v47, v128, v129
	v_cvt_pk_bf16_f32 v48, v130, v131
	v_cvt_pk_bf16_f32 v49, v132, v133
	v_cvt_pk_bf16_f32 v50, v134, v135
	v_cvt_pk_bf16_f32 v51, v136, v122
	s_and_b64 s[74:75], s[50:51], s[0:1]
	v_permlane32_swap_b32_e32 v40, v42
	v_permlane32_swap_b32_e32 v41, v43
	v_permlane32_swap_b32_e32 v44, v46
	v_permlane32_swap_b32_e32 v45, v47
	v_permlane32_swap_b32_e32 v48, v50
	v_permlane32_swap_b32_e32 v49, v51
	ds_write_b128 v179, v[36:39] offset:16384
	ds_write_b128 v179, v[40:43] offset:17408
	ds_write_b128 v179, v[44:47] offset:18432
	ds_write_b128 v179, v[48:51] offset:19456
	s_and_saveexec_b64 s[52:53], s[74:75]
	ds_write_b32 v117, v99 offset:1024
	s_or_b64 exec, exec, s[52:53]
	s_and_saveexec_b64 s[52:53], s[4:5]
	s_cbranch_execz .LBB0_507
	v_cndmask_b32_e64 v36, 0, 1.0, s[50:51]
	v_mov_b32_e32 v37, s65
	ds_write_b32 v37, v36 offset:1152
	s_branch .LBB0_507

; __global__ void __launch_bounds__(512, 2) mk_fwd(Args a) {
;     extern __shared__ __attribute__((aligned(16))) unsigned char lds_g[];
	.amdhsa_kernel _Z6mk_fwd4Args
		.amdhsa_group_segment_fixed_size 0
		.amdhsa_private_segment_fixed_size 0
		.amdhsa_kernarg_size 392
		.amdhsa_user_sgpr_count 2
		.amdhsa_user_sgpr_dispatch_ptr 0
		.amdhsa_user_sgpr_queue_ptr 0
		.amdhsa_user_sgpr_kernarg_segment_ptr 1
		.amdhsa_user_sgpr_dispatch_id 0
		.amdhsa_user_sgpr_kernarg_preload_length 0
		.amdhsa_user_sgpr_kernarg_preload_offset 0
		.amdhsa_user_sgpr_private_segment_size 0
		.amdhsa_uses_dynamic_stack 0
		.amdhsa_enable_private_segment 0
		.amdhsa_system_sgpr_workgroup_id_x 1
		.amdhsa_system_sgpr_workgroup_id_y 0
		.amdhsa_system_sgpr_workgroup_id_z 0
		.amdhsa_system_sgpr_workgroup_info 0
		.amdhsa_system_vgpr_workitem_id 2
		.amdhsa_next_free_vgpr 256
		.amdhsa_next_free_sgpr 100
		.amdhsa_accum_offset 256
		.amdhsa_reserve_vcc 1
		.amdhsa_float_round_mode_32 0
		.amdhsa_float_round_mode_16_64 0
		.amdhsa_float_denorm_mode_32 3
		.amdhsa_float_denorm_mode_16_64 3
		.amdhsa_dx10_clamp 1
		.amdhsa_ieee_mode 1
		.amdhsa_fp16_overflow 0
		.amdhsa_tg_split 0
		.amdhsa_exception_fp_ieee_invalid_op 0
		.amdhsa_exception_fp_denorm_src 0
		.amdhsa_exception_fp_ieee_div_zero 0
		.amdhsa_exception_fp_ieee_overflow 0
		.amdhsa_exception_fp_ieee_underflow 0
		.amdhsa_exception_fp_ieee_inexact 0
		.amdhsa_exception_int_div_zero 0
	.end_amdhsa_kernel

; __global__ void __launch_bounds__(512, 2) mk_fwd(Args a) {
;     extern __shared__ __attribute__((aligned(16))) unsigned char lds_g[];
amdhsa.kernels:
  - .agpr_count:     0
    .args:
      - .offset:         0
        .size:           136
        .value_kind:     by_value
      - .offset:         136
        .size:           4
        .value_kind:     hidden_block_count_x
      - .offset:         140
        .size:           4
        .value_kind:     hidden_block_count_y
      - .offset:         144
        .size:           4
        .value_kind:     hidden_block_count_z
      - .offset:         148
        .size:           2
        .value_kind:     hidden_group_size_x
      - .offset:         150
        .size:           2
        .value_kind:     hidden_group_size_y
      - .offset:         152
        .size:           2
        .value_kind:     hidden_group_size_z
      - .offset:         154
        .size:           2
        .value_kind:     hidden_remainder_x
      - .offset:         156
        .size:           2
        .value_kind:     hidden_remainder_y
      - .offset:         158
        .size:           2
        .value_kind:     hidden_remainder_z
      - .offset:         176
        .size:           8
        .value_kind:     hidden_global_offset_x
      - .offset:         184
        .size:           8
        .value_kind:     hidden_global_offset_y
      - .offset:         192
        .size:           8
        .value_kind:     hidden_global_offset_z
      - .offset:         200
        .size:           2
        .value_kind:     hidden_grid_dims
      - .offset:         224
        .size:           8
        .value_kind:     hidden_multigrid_sync_arg
      - .offset:         256
        .size:           4
        .value_kind:     hidden_dynamic_lds_size
    .group_segment_fixed_size: 0
    .kernarg_segment_align: 8
    .kernarg_segment_size: 392
    .language:       OpenCL C
    .language_version:
      - 2
      - 0
    .max_flat_workgroup_size: 512
    .name:           _Z6mk_fwd4Args
    .private_segment_fixed_size: 0
    .sgpr_count:     106
    .sgpr_spill_count: 41
    .symbol:         _Z6mk_fwd4Args.kd
    .uniform_work_group_size: 1
    .uses_dynamic_stack: false
    .vgpr_count:     256
    .vgpr_spill_count: 0
    .wavefront_size: 64
